# LDS-DMA saddr addressing now in all eight 2-K-tile GEMM loops (128 64-bit VALU adds per iteration removed)
# speedup vs baseline: 1.0172x; 1.0002x over previous
.LBB0_279:
	s_add_u32 s12, s10, 0xfffc0080
	s_addc_u32 s13, s11, -1
	s_add_i32 s19, 0, 0x10000
	v_add_u32_e32 v140, s19, v188
	ds_read_b128 v[120:123], v140
	ds_read_b128 v[124:127], v140 offset:1024
	ds_read_b128 v[136:139], v140 offset:2048
	ds_read_b128 v[140:143], v140 offset:3072
	s_cmp_eq_u32 s18, 12
	s_cselect_b32 s15, s0, s13
	s_cselect_b32 s14, s1, s12
	s_cselect_b32 s13, s7, s17
	s_cselect_b32 s12, s9, s16
	s_add_i32 m0, s68, 0xc000
	ds_read_b128 v[144:147], v189
	ds_read_b128 v[148:151], v189 offset:1024
	ds_read_b128 v[152:155], v189 offset:2048
	ds_read_b128 v[156:159], v189 offset:3072
	ds_read_b128 v[168:171], v189 offset:4096
	ds_read_b128 v[172:175], v189 offset:5120
	ds_read_b128 v[176:179], v189 offset:6144
	ds_read_b128 v[180:183], v189 offset:7168
	global_load_lds_dwordx4 v166, s[10:11]
	s_add_i32 m0, s68, 0xe000
	s_nop 0
	global_load_lds_dwordx4 v164, s[10:11]
	s_waitcnt lgkmcnt(8)
	s_barrier
	s_waitcnt lgkmcnt(0)
	s_setprio 1
	s_waitcnt lgkmcnt(0)
	v_mfma_f32_16x16x32_bf16 v[132:135], v[120:123], v[144:147], v[132:135]
	v_mfma_f32_16x16x32_bf16 v[128:131], v[136:139], v[144:147], v[128:131]
	v_mfma_f32_16x16x32_bf16 v[108:111], v[120:123], v[152:155], v[108:111]
	v_mfma_f32_16x16x32_bf16 v[104:107], v[136:139], v[152:155], v[104:107]
	v_mfma_f32_16x16x32_bf16 v[92:95], v[120:123], v[168:171], v[92:95]
	v_mfma_f32_16x16x32_bf16 v[88:91], v[136:139], v[168:171], v[88:91]
	v_mfma_f32_16x16x32_bf16 v[76:79], v[120:123], v[176:179], v[76:79]
	v_mfma_f32_16x16x32_bf16 v[72:75], v[136:139], v[176:179], v[72:75]
	v_mfma_f32_16x16x32_bf16 v[132:135], v[124:127], v[148:151], v[132:135]
	v_mfma_f32_16x16x32_bf16 v[128:131], v[140:143], v[148:151], v[128:131]
	v_mfma_f32_16x16x32_bf16 v[108:111], v[124:127], v[156:159], v[108:111]
	v_mfma_f32_16x16x32_bf16 v[104:107], v[140:143], v[156:159], v[104:107]
	v_mfma_f32_16x16x32_bf16 v[92:95], v[124:127], v[172:175], v[92:95]
	v_mfma_f32_16x16x32_bf16 v[88:91], v[140:143], v[172:175], v[88:91]
	v_mfma_f32_16x16x32_bf16 v[76:79], v[124:127], v[180:183], v[76:79]
	v_mfma_f32_16x16x32_bf16 v[72:75], v[140:143], v[180:183], v[72:75]
	s_setprio 0
	s_barrier
	s_add_i32 s33, 0, 0x14000
	v_add_u32_e32 v190, s33, v188
	s_add_i32 s19, s19, s67
	ds_read_b128 v[184:187], v190
	ds_read_b128 v[198:201], v190 offset:1024
	ds_read_b128 v[206:209], v190 offset:2048
	ds_read_b128 v[210:213], v190 offset:3072
	s_mov_b32 m0, s19
	s_nop 0
	global_load_lds_dwordx4 v160, s[12:13]
	s_add_i32 m0, s19, 0x2000
	s_nop 0
	global_load_lds_dwordx4 v162, s[12:13]
	s_barrier
	s_waitcnt lgkmcnt(0)
	s_setprio 1
	s_waitcnt lgkmcnt(0)
	v_mfma_f32_16x16x32_bf16 v[116:119], v[184:187], v[144:147], v[116:119]
	v_mfma_f32_16x16x32_bf16 v[112:115], v[206:209], v[144:147], v[112:115]
	v_mfma_f32_16x16x32_bf16 v[100:103], v[184:187], v[152:155], v[100:103]
	v_mfma_f32_16x16x32_bf16 v[96:99], v[206:209], v[152:155], v[96:99]
	v_mfma_f32_16x16x32_bf16 v[84:87], v[184:187], v[168:171], v[84:87]
	v_mfma_f32_16x16x32_bf16 v[80:83], v[206:209], v[168:171], v[80:83]
	v_mfma_f32_16x16x32_bf16 v[68:71], v[184:187], v[176:179], v[68:71]
	v_mfma_f32_16x16x32_bf16 v[64:67], v[206:209], v[176:179], v[64:67]
	v_mfma_f32_16x16x32_bf16 v[116:119], v[198:201], v[148:151], v[116:119]
	v_mfma_f32_16x16x32_bf16 v[112:115], v[210:213], v[148:151], v[112:115]
	v_mfma_f32_16x16x32_bf16 v[100:103], v[198:201], v[156:159], v[100:103]
	v_mfma_f32_16x16x32_bf16 v[96:99], v[210:213], v[156:159], v[96:99]
	v_mfma_f32_16x16x32_bf16 v[84:87], v[198:201], v[172:175], v[84:87]
	v_mfma_f32_16x16x32_bf16 v[80:83], v[210:213], v[172:175], v[80:83]
	v_mfma_f32_16x16x32_bf16 v[68:71], v[198:201], v[180:183], v[68:71]
	v_mfma_f32_16x16x32_bf16 v[64:67], v[210:213], v[180:183], v[64:67]
	s_setprio 0
	s_mov_b32 m0, s68
	s_add_u32 vcc_lo, s14, 0x80
	s_addc_u32 vcc_hi, s15, 0
	s_barrier
	ds_read_b128 v[144:147], v189 offset:16384
	ds_read_b128 v[148:151], v189 offset:17408
	ds_read_b128 v[152:155], v189 offset:18432
	ds_read_b128 v[156:159], v189 offset:19456
	ds_read_b128 v[168:171], v189 offset:20480
	ds_read_b128 v[172:175], v189 offset:21504
	ds_read_b128 v[176:179], v189 offset:22528
	ds_read_b128 v[180:183], v189 offset:23552
	global_load_lds_dwordx4 v160, s[14:15]
	s_mov_b32 m0, s69
	s_nop 0
	global_load_lds_dwordx4 v162, s[14:15]
	s_barrier
	s_waitcnt lgkmcnt(0)
	s_setprio 1
	s_waitcnt lgkmcnt(0)
	v_mfma_f32_16x16x32_bf16 v[60:63], v[120:123], v[144:147], v[60:63]
	v_mfma_f32_16x16x32_bf16 v[56:59], v[136:139], v[144:147], v[56:59]
	v_mfma_f32_16x16x32_bf16 v[44:47], v[120:123], v[152:155], v[44:47]
	v_mfma_f32_16x16x32_bf16 v[40:43], v[136:139], v[152:155], v[40:43]
	v_mfma_f32_16x16x32_bf16 v[28:31], v[120:123], v[168:171], v[28:31]
	v_mfma_f32_16x16x32_bf16 v[24:27], v[136:139], v[168:171], v[24:27]
	v_mfma_f32_16x16x32_bf16 v[12:15], v[120:123], v[176:179], v[12:15]
	v_mfma_f32_16x16x32_bf16 v[8:11], v[136:139], v[176:179], v[8:11]
	v_mfma_f32_16x16x32_bf16 v[60:63], v[124:127], v[148:151], v[60:63]
	v_mfma_f32_16x16x32_bf16 v[56:59], v[140:143], v[148:151], v[56:59]
	v_mfma_f32_16x16x32_bf16 v[44:47], v[124:127], v[156:159], v[44:47]
	v_mfma_f32_16x16x32_bf16 v[40:43], v[140:143], v[156:159], v[40:43]
	v_mfma_f32_16x16x32_bf16 v[28:31], v[124:127], v[172:175], v[28:31]
	v_mfma_f32_16x16x32_bf16 v[24:27], v[140:143], v[172:175], v[24:27]
	v_mfma_f32_16x16x32_bf16 v[12:15], v[124:127], v[180:183], v[12:15]
	v_mfma_f32_16x16x32_bf16 v[8:11], v[140:143], v[180:183], v[8:11]
	s_setprio 0
	s_barrier
	s_add_u32 s44, s12, 0x40000
	s_addc_u32 s45, s13, 0
	s_add_i32 s19, s33, s67
	s_mov_b32 m0, s19
	s_nop 0
	global_load_lds_dwordx4 v160, s[44:45]
	s_add_i32 m0, s19, 0x2000
	s_nop 0
	global_load_lds_dwordx4 v162, s[44:45]
	s_waitcnt vmcnt(6)
	s_barrier
	s_setprio 1
	v_mfma_f32_16x16x32_bf16 v[52:55], v[184:187], v[144:147], v[52:55]
	v_mfma_f32_16x16x32_bf16 v[48:51], v[206:209], v[144:147], v[48:51]
	v_mfma_f32_16x16x32_bf16 v[36:39], v[184:187], v[152:155], v[36:39]
	v_mfma_f32_16x16x32_bf16 v[32:35], v[206:209], v[152:155], v[32:35]
	v_mfma_f32_16x16x32_bf16 v[20:23], v[184:187], v[168:171], v[20:23]
	v_mfma_f32_16x16x32_bf16 v[16:19], v[206:209], v[168:171], v[16:19]
	v_mfma_f32_16x16x32_bf16 v[4:7], v[184:187], v[176:179], v[4:7]
	v_mfma_f32_16x16x32_bf16 v[0:3], v[206:209], v[176:179], v[0:3]
	v_mfma_f32_16x16x32_bf16 v[52:55], v[198:201], v[148:151], v[52:55]
	v_mfma_f32_16x16x32_bf16 v[48:51], v[210:213], v[148:151], v[48:51]
	v_mfma_f32_16x16x32_bf16 v[36:39], v[198:201], v[156:159], v[36:39]
	v_mfma_f32_16x16x32_bf16 v[32:35], v[210:213], v[156:159], v[32:35]
	v_mfma_f32_16x16x32_bf16 v[20:23], v[198:201], v[172:175], v[20:23]
	v_mfma_f32_16x16x32_bf16 v[16:19], v[210:213], v[172:175], v[16:19]
	v_mfma_f32_16x16x32_bf16 v[4:7], v[198:201], v[180:183], v[4:7]
	v_mfma_f32_16x16x32_bf16 v[0:3], v[210:213], v[180:183], v[0:3]
	s_setprio 0
	s_add_i32 s19, 0, 0x18000
	v_add_u32_e32 v140, s19, v188
	s_barrier
	ds_read_b128 v[120:123], v140
	ds_read_b128 v[124:127], v140 offset:1024
	ds_read_b128 v[136:139], v140 offset:2048
	ds_read_b128 v[140:143], v140 offset:3072
	s_add_u32 s14, s14, 0x40000
	s_addc_u32 s15, s15, 0
	s_mov_b32 m0, s72
	ds_read_b128 v[144:147], v189 offset:32768
	ds_read_b128 v[148:151], v189 offset:33792
	ds_read_b128 v[152:155], v189 offset:34816
	ds_read_b128 v[156:159], v189 offset:35840
	ds_read_b128 v[168:171], v189 offset:36864
	ds_read_b128 v[172:175], v189 offset:37888
	ds_read_b128 v[176:179], v189 offset:38912
	ds_read_b128 v[180:183], v189 offset:39936
	global_load_lds_dwordx4 v160, s[14:15]
	s_mov_b32 m0, s73
	s_nop 0
	global_load_lds_dwordx4 v162, s[14:15]
	s_waitcnt lgkmcnt(8)
	s_barrier
	s_waitcnt lgkmcnt(0)
	s_setprio 1
	s_waitcnt lgkmcnt(0)
	v_mfma_f32_16x16x32_bf16 v[132:135], v[120:123], v[144:147], v[132:135]
	v_mfma_f32_16x16x32_bf16 v[128:131], v[136:139], v[144:147], v[128:131]
	v_mfma_f32_16x16x32_bf16 v[108:111], v[120:123], v[152:155], v[108:111]
	v_mfma_f32_16x16x32_bf16 v[104:107], v[136:139], v[152:155], v[104:107]
	v_mfma_f32_16x16x32_bf16 v[92:95], v[120:123], v[168:171], v[92:95]
	v_mfma_f32_16x16x32_bf16 v[88:91], v[136:139], v[168:171], v[88:91]
	v_mfma_f32_16x16x32_bf16 v[76:79], v[120:123], v[176:179], v[76:79]
	v_mfma_f32_16x16x32_bf16 v[72:75], v[136:139], v[176:179], v[72:75]
	v_mfma_f32_16x16x32_bf16 v[132:135], v[124:127], v[148:151], v[132:135]
	v_mfma_f32_16x16x32_bf16 v[128:131], v[140:143], v[148:151], v[128:131]
	v_mfma_f32_16x16x32_bf16 v[108:111], v[124:127], v[156:159], v[108:111]
	v_mfma_f32_16x16x32_bf16 v[104:107], v[140:143], v[156:159], v[104:107]
	v_mfma_f32_16x16x32_bf16 v[92:95], v[124:127], v[172:175], v[92:95]
	v_mfma_f32_16x16x32_bf16 v[88:91], v[140:143], v[172:175], v[88:91]
	v_mfma_f32_16x16x32_bf16 v[76:79], v[124:127], v[180:183], v[76:79]
	v_mfma_f32_16x16x32_bf16 v[72:75], v[140:143], v[180:183], v[72:75]
	s_setprio 0
	s_barrier
	s_add_i32 s14, 0, 0x1c000
	s_add_i32 s15, s19, s67
	v_add_u32_e32 v192, s14, v188
	s_add_u32 s100, s12, 0x80
	s_addc_u32 s101, s13, 0
	s_mov_b32 m0, s15
	ds_read_b128 v[184:187], v192
	ds_read_b128 v[198:201], v192 offset:1024
	ds_read_b128 v[206:209], v192 offset:2048
	ds_read_b128 v[210:213], v192 offset:3072
	global_load_lds_dwordx4 v160, s[100:101]
	s_add_i32 m0, s15, 0x2000
	s_nop 0
	global_load_lds_dwordx4 v162, s[100:101]
	s_barrier
	s_waitcnt lgkmcnt(0)
	s_setprio 1
	s_waitcnt lgkmcnt(0)
	v_mfma_f32_16x16x32_bf16 v[116:119], v[184:187], v[144:147], v[116:119]
	v_mfma_f32_16x16x32_bf16 v[112:115], v[206:209], v[144:147], v[112:115]
	v_mfma_f32_16x16x32_bf16 v[100:103], v[184:187], v[152:155], v[100:103]
	v_mfma_f32_16x16x32_bf16 v[96:99], v[206:209], v[152:155], v[96:99]
	v_mfma_f32_16x16x32_bf16 v[84:87], v[184:187], v[168:171], v[84:87]
	v_mfma_f32_16x16x32_bf16 v[80:83], v[206:209], v[168:171], v[80:83]
	v_mfma_f32_16x16x32_bf16 v[68:71], v[184:187], v[176:179], v[68:71]
	v_mfma_f32_16x16x32_bf16 v[64:67], v[206:209], v[176:179], v[64:67]
	v_mfma_f32_16x16x32_bf16 v[116:119], v[198:201], v[148:151], v[116:119]
	v_mfma_f32_16x16x32_bf16 v[112:115], v[210:213], v[148:151], v[112:115]
	v_mfma_f32_16x16x32_bf16 v[100:103], v[198:201], v[156:159], v[100:103]
	v_mfma_f32_16x16x32_bf16 v[96:99], v[210:213], v[156:159], v[96:99]
	v_mfma_f32_16x16x32_bf16 v[84:87], v[198:201], v[172:175], v[84:87]
	v_mfma_f32_16x16x32_bf16 v[80:83], v[210:213], v[172:175], v[80:83]
	v_mfma_f32_16x16x32_bf16 v[68:71], v[198:201], v[180:183], v[68:71]
	v_mfma_f32_16x16x32_bf16 v[64:67], v[210:213], v[180:183], v[64:67]
	s_setprio 0
	s_mov_b32 m0, s74
	s_barrier
	ds_read_b128 v[144:147], v189 offset:49152
	ds_read_b128 v[148:151], v189 offset:50176
	ds_read_b128 v[152:155], v189 offset:51200
	ds_read_b128 v[156:159], v189 offset:52224
	ds_read_b128 v[168:171], v189 offset:53248
	ds_read_b128 v[172:175], v189 offset:54272
	ds_read_b128 v[176:179], v189 offset:55296
	ds_read_b128 v[180:183], v189 offset:56320
	global_load_lds_dwordx4 v160, vcc
	s_mov_b32 m0, s75
	s_nop 0
	global_load_lds_dwordx4 v162, vcc
	s_barrier
	s_waitcnt lgkmcnt(0)
	s_setprio 1
	s_waitcnt lgkmcnt(0)
	v_mfma_f32_16x16x32_bf16 v[60:63], v[120:123], v[144:147], v[60:63]
	v_mfma_f32_16x16x32_bf16 v[56:59], v[136:139], v[144:147], v[56:59]
	v_mfma_f32_16x16x32_bf16 v[44:47], v[120:123], v[152:155], v[44:47]
	v_mfma_f32_16x16x32_bf16 v[40:43], v[136:139], v[152:155], v[40:43]
	v_mfma_f32_16x16x32_bf16 v[28:31], v[120:123], v[168:171], v[28:31]
	v_mfma_f32_16x16x32_bf16 v[24:27], v[136:139], v[168:171], v[24:27]
	v_mfma_f32_16x16x32_bf16 v[12:15], v[120:123], v[176:179], v[12:15]
	v_mfma_f32_16x16x32_bf16 v[8:11], v[136:139], v[176:179], v[8:11]
	v_mfma_f32_16x16x32_bf16 v[60:63], v[124:127], v[148:151], v[60:63]
	v_mfma_f32_16x16x32_bf16 v[56:59], v[140:143], v[148:151], v[56:59]
	v_mfma_f32_16x16x32_bf16 v[44:47], v[124:127], v[156:159], v[44:47]
	v_mfma_f32_16x16x32_bf16 v[40:43], v[140:143], v[156:159], v[40:43]
	v_mfma_f32_16x16x32_bf16 v[28:31], v[124:127], v[172:175], v[28:31]
	v_mfma_f32_16x16x32_bf16 v[24:27], v[140:143], v[172:175], v[24:27]
	v_mfma_f32_16x16x32_bf16 v[12:15], v[124:127], v[180:183], v[12:15]
	v_mfma_f32_16x16x32_bf16 v[8:11], v[140:143], v[180:183], v[8:11]
	s_setprio 0
	s_barrier
	s_add_u32 s12, s12, 0x40080
	s_addc_u32 s13, s13, 0
	s_add_i32 s14, s14, s67
	s_mov_b32 m0, s14
	s_nop 0
	global_load_lds_dwordx4 v160, s[12:13]
	s_add_i32 m0, s14, 0x2000
	s_nop 0
	global_load_lds_dwordx4 v162, s[12:13]
	s_waitcnt vmcnt(6)
	s_barrier
	s_setprio 1
	v_mfma_f32_16x16x32_bf16 v[52:55], v[184:187], v[144:147], v[52:55]
	v_mfma_f32_16x16x32_bf16 v[48:51], v[206:209], v[144:147], v[48:51]
	v_mfma_f32_16x16x32_bf16 v[36:39], v[184:187], v[152:155], v[36:39]
	v_mfma_f32_16x16x32_bf16 v[32:35], v[206:209], v[152:155], v[32:35]
	v_mfma_f32_16x16x32_bf16 v[20:23], v[184:187], v[168:171], v[20:23]
	v_mfma_f32_16x16x32_bf16 v[16:19], v[206:209], v[168:171], v[16:19]
	v_mfma_f32_16x16x32_bf16 v[4:7], v[184:187], v[176:179], v[4:7]
	v_mfma_f32_16x16x32_bf16 v[0:3], v[206:209], v[176:179], v[0:3]
	v_mfma_f32_16x16x32_bf16 v[52:55], v[198:201], v[148:151], v[52:55]
	v_mfma_f32_16x16x32_bf16 v[48:51], v[210:213], v[148:151], v[48:51]
	v_mfma_f32_16x16x32_bf16 v[36:39], v[198:201], v[156:159], v[36:39]
	v_mfma_f32_16x16x32_bf16 v[32:35], v[210:213], v[156:159], v[32:35]
	v_mfma_f32_16x16x32_bf16 v[20:23], v[198:201], v[172:175], v[20:23]
	v_mfma_f32_16x16x32_bf16 v[16:19], v[210:213], v[172:175], v[16:19]
	v_mfma_f32_16x16x32_bf16 v[4:7], v[198:201], v[180:183], v[4:7]
	v_mfma_f32_16x16x32_bf16 v[0:3], v[210:213], v[180:183], v[0:3]
	s_setprio 0
	s_add_i32 s18, s18, 2
	s_add_u32 s16, s16, 0x100
	s_addc_u32 s17, s17, 0
	s_add_u32 s10, s10, 0x100
	s_addc_u32 s11, s11, 0
	s_cmp_gt_u32 s18, 13
	s_barrier
	s_cbranch_scc0 .LBB0_279
	v_mov_b32_e32 v120, v252
	s_lshl_b32 s0, s8, 8
	v_readfirstlane_b32 s1, v120
	s_ashr_i32 s7, s1, 2
	s_andn2_b32 s7, s7, 63
	v_and_b32_e32 v121, 15, v120
	s_add_i32 s0, s7, s0
	v_or_b32_e32 v172, s0, v121
	v_ashrrev_i32_e32 v173, 31, v172
	v_lshl_add_u64 v[174:175], v[172:173], 2, s[34:35]
	global_load_dword v171, v[174:175], off
	s_lshr_b32 s1, s1, 1
	s_and_b32 s1, s1, 0x60
	s_lshl_b32 s6, s6, 8
	s_or_b32 s1, s1, s6
	v_lshrrev_b32_e32 v120, 2, v120
	s_cmpk_eq_i32 s1, 0x100
	v_and_b32_e32 v170, 12, v120
	s_movk_i32 s6, 0x4000
	v_mov_b32_e32 v120, 0x1fcf
	s_cselect_b64 s[8:9], -1, 0
	v_lshlrev_b32_e32 v168, 1, v170
	v_cmp_gt_i32_e64 s[10:11], s6, v172
	v_bitop3_b32 v169, s0, v120, v121 bitop3:0xc8
	v_mov_b32_e32 v144, 0
	s_and_b64 vcc, exec, s[8:9]
	v_mov_b32_e32 v152, 0
	v_mov_b32_e32 v153, 0
	v_mov_b32_e32 v154, 0
	v_mov_b32_e32 v155, 0
	v_mov_b32_e32 v156, 0
	v_mov_b32_e32 v157, 0
	v_mov_b32_e32 v158, 0
	v_mov_b32_e32 v159, 0
	s_cbranch_vccz .LBB0_282
	v_or_b32_e32 v120, 16, v169
	v_add_u32_e32 v121, 0x7ffc000, v172
	v_cndmask_b32_e64 v120, v121, v120, s[10:11]
	v_lshl_or_b32 v192, v120, 5, v168
	v_lshl_add_u64 v[120:121], v[192:193], 2, s[30:31]
	global_load_dwordx4 v[152:155], v[120:121], off
	global_load_dwordx4 v[156:159], v[120:121], off offset:16

.LBB0_2148:
	s_add_u32 s34, s30, 0xfffc0080
	s_addc_u32 s35, s31, -1
	s_add_i32 s51, 0, 0x10000
	v_add_u32_e32 v146, s51, v148
	ds_read_b128 v[138:141], v146
	ds_read_b128 v[142:145], v146 offset:1024
	ds_read_b128 v[150:153], v146 offset:2048
	ds_read_b128 v[154:157], v146 offset:3072
	s_cmp_eq_u32 s33, 12
	s_cselect_b32 s37, s0, s35
	s_cselect_b32 s36, s1, s34
	s_cselect_b32 s35, s7, s25
	s_cselect_b32 s34, s9, s19
	s_add_i32 m0, s44, 0xc000
	ds_read_b128 v[158:161], v149
	ds_read_b128 v[162:165], v149 offset:1024
	ds_read_b128 v[166:169], v149 offset:2048
	ds_read_b128 v[170:173], v149 offset:3072
	ds_read_b128 v[174:177], v149 offset:4096
	ds_read_b128 v[178:181], v149 offset:5120
	ds_read_b128 v[182:185], v149 offset:6144
	ds_read_b128 v[186:189], v149 offset:7168
	global_load_lds_dwordx4 v134, s[30:31]
	s_add_i32 m0, s44, 0xe000
	s_nop 0
	global_load_lds_dwordx4 v136, s[30:31]
	s_waitcnt lgkmcnt(8)
	s_barrier
	s_waitcnt lgkmcnt(0)
	s_setprio 1
	s_waitcnt lgkmcnt(0)
	v_mfma_f32_16x16x32_bf16 v[124:127], v[138:141], v[158:161], v[124:127]
	v_mfma_f32_16x16x32_bf16 v[120:123], v[150:153], v[158:161], v[120:123]
	v_mfma_f32_16x16x32_bf16 v[108:111], v[138:141], v[166:169], v[108:111]
	v_mfma_f32_16x16x32_bf16 v[104:107], v[150:153], v[166:169], v[104:107]
	v_mfma_f32_16x16x32_bf16 v[92:95], v[138:141], v[174:177], v[92:95]
	v_mfma_f32_16x16x32_bf16 v[88:91], v[150:153], v[174:177], v[88:91]
	v_mfma_f32_16x16x32_bf16 v[76:79], v[138:141], v[182:185], v[76:79]
	v_mfma_f32_16x16x32_bf16 v[72:75], v[150:153], v[182:185], v[72:75]
	v_mfma_f32_16x16x32_bf16 v[124:127], v[142:145], v[162:165], v[124:127]
	v_mfma_f32_16x16x32_bf16 v[120:123], v[154:157], v[162:165], v[120:123]
	v_mfma_f32_16x16x32_bf16 v[108:111], v[142:145], v[170:173], v[108:111]
	v_mfma_f32_16x16x32_bf16 v[104:107], v[154:157], v[170:173], v[104:107]
	v_mfma_f32_16x16x32_bf16 v[92:95], v[142:145], v[178:181], v[92:95]
	v_mfma_f32_16x16x32_bf16 v[88:91], v[154:157], v[178:181], v[88:91]
	v_mfma_f32_16x16x32_bf16 v[76:79], v[142:145], v[186:189], v[76:79]
	v_mfma_f32_16x16x32_bf16 v[72:75], v[154:157], v[186:189], v[72:75]
	s_setprio 0
	s_barrier
	s_add_i32 s54, 0, 0x14000
	v_add_u32_e32 v146, s54, v148
	s_add_i32 s51, s51, s43
	ds_read_b128 v[198:201], v146
	ds_read_b128 v[206:209], v146 offset:1024
	ds_read_b128 v[210:213], v146 offset:2048
	ds_read_b128 v[214:217], v146 offset:3072
	s_mov_b32 m0, s51
	s_nop 0
	global_load_lds_dwordx4 v192, s[34:35]
	s_add_i32 m0, s51, 0x2000
	s_nop 0
	global_load_lds_dwordx4 v132, s[34:35]
	s_barrier
	s_waitcnt lgkmcnt(0)
	s_setprio 1
	s_waitcnt lgkmcnt(0)
	v_mfma_f32_16x16x32_bf16 v[116:119], v[198:201], v[158:161], v[116:119]
	v_mfma_f32_16x16x32_bf16 v[112:115], v[210:213], v[158:161], v[112:115]
	v_mfma_f32_16x16x32_bf16 v[100:103], v[198:201], v[166:169], v[100:103]
	v_mfma_f32_16x16x32_bf16 v[96:99], v[210:213], v[166:169], v[96:99]
	v_mfma_f32_16x16x32_bf16 v[84:87], v[198:201], v[174:177], v[84:87]
	v_mfma_f32_16x16x32_bf16 v[80:83], v[210:213], v[174:177], v[80:83]
	v_mfma_f32_16x16x32_bf16 v[68:71], v[198:201], v[182:185], v[68:71]
	v_mfma_f32_16x16x32_bf16 v[64:67], v[210:213], v[182:185], v[64:67]
	v_mfma_f32_16x16x32_bf16 v[116:119], v[206:209], v[162:165], v[116:119]
	v_mfma_f32_16x16x32_bf16 v[112:115], v[214:217], v[162:165], v[112:115]
	v_mfma_f32_16x16x32_bf16 v[100:103], v[206:209], v[170:173], v[100:103]
	v_mfma_f32_16x16x32_bf16 v[96:99], v[214:217], v[170:173], v[96:99]
	v_mfma_f32_16x16x32_bf16 v[84:87], v[206:209], v[178:181], v[84:87]
	v_mfma_f32_16x16x32_bf16 v[80:83], v[214:217], v[178:181], v[80:83]
	v_mfma_f32_16x16x32_bf16 v[68:71], v[206:209], v[186:189], v[68:71]
	v_mfma_f32_16x16x32_bf16 v[64:67], v[214:217], v[186:189], v[64:67]
	s_setprio 0
	s_mov_b32 m0, s44
	s_add_u32 vcc_lo, s36, 0x80
	s_addc_u32 vcc_hi, s37, 0
	s_barrier
	ds_read_b128 v[158:161], v149 offset:16384
	ds_read_b128 v[162:165], v149 offset:17408
	ds_read_b128 v[166:169], v149 offset:18432
	ds_read_b128 v[170:173], v149 offset:19456
	ds_read_b128 v[174:177], v149 offset:20480
	ds_read_b128 v[178:181], v149 offset:21504
	ds_read_b128 v[182:185], v149 offset:22528
	ds_read_b128 v[186:189], v149 offset:23552
	global_load_lds_dwordx4 v128, s[36:37]
	s_mov_b32 m0, s45
	s_nop 0
	global_load_lds_dwordx4 v130, s[36:37]
	s_barrier
	s_waitcnt lgkmcnt(0)
	s_setprio 1
	s_waitcnt lgkmcnt(0)
	v_mfma_f32_16x16x32_bf16 v[60:63], v[138:141], v[158:161], v[60:63]
	v_mfma_f32_16x16x32_bf16 v[56:59], v[150:153], v[158:161], v[56:59]
	v_mfma_f32_16x16x32_bf16 v[44:47], v[138:141], v[166:169], v[44:47]
	v_mfma_f32_16x16x32_bf16 v[40:43], v[150:153], v[166:169], v[40:43]
	v_mfma_f32_16x16x32_bf16 v[28:31], v[138:141], v[174:177], v[28:31]
	v_mfma_f32_16x16x32_bf16 v[24:27], v[150:153], v[174:177], v[24:27]
	v_mfma_f32_16x16x32_bf16 v[12:15], v[138:141], v[182:185], v[12:15]
	v_mfma_f32_16x16x32_bf16 v[8:11], v[150:153], v[182:185], v[8:11]
	v_mfma_f32_16x16x32_bf16 v[60:63], v[142:145], v[162:165], v[60:63]
	v_mfma_f32_16x16x32_bf16 v[56:59], v[154:157], v[162:165], v[56:59]
	v_mfma_f32_16x16x32_bf16 v[44:47], v[142:145], v[170:173], v[44:47]
	v_mfma_f32_16x16x32_bf16 v[40:43], v[154:157], v[170:173], v[40:43]
	v_mfma_f32_16x16x32_bf16 v[28:31], v[142:145], v[178:181], v[28:31]
	v_mfma_f32_16x16x32_bf16 v[24:27], v[154:157], v[178:181], v[24:27]
	v_mfma_f32_16x16x32_bf16 v[12:15], v[142:145], v[186:189], v[12:15]
	v_mfma_f32_16x16x32_bf16 v[8:11], v[154:157], v[186:189], v[8:11]
	s_setprio 0
	s_barrier
	s_add_u32 s52, s34, 0x40000
	s_addc_u32 s53, s35, 0
	s_add_i32 s51, s54, s43
	s_mov_b32 m0, s51
	s_nop 0
	global_load_lds_dwordx4 v192, s[52:53]
	s_add_i32 m0, s51, 0x2000
	s_nop 0
	global_load_lds_dwordx4 v132, s[52:53]
	s_waitcnt vmcnt(6)
	s_barrier
	s_setprio 1
	v_mfma_f32_16x16x32_bf16 v[52:55], v[198:201], v[158:161], v[52:55]
	v_mfma_f32_16x16x32_bf16 v[48:51], v[210:213], v[158:161], v[48:51]
	v_mfma_f32_16x16x32_bf16 v[36:39], v[198:201], v[166:169], v[36:39]
	v_mfma_f32_16x16x32_bf16 v[32:35], v[210:213], v[166:169], v[32:35]
	v_mfma_f32_16x16x32_bf16 v[20:23], v[198:201], v[174:177], v[20:23]
	v_mfma_f32_16x16x32_bf16 v[16:19], v[210:213], v[174:177], v[16:19]
	v_mfma_f32_16x16x32_bf16 v[4:7], v[198:201], v[182:185], v[4:7]
	v_mfma_f32_16x16x32_bf16 v[0:3], v[210:213], v[182:185], v[0:3]
	v_mfma_f32_16x16x32_bf16 v[52:55], v[206:209], v[162:165], v[52:55]
	v_mfma_f32_16x16x32_bf16 v[48:51], v[214:217], v[162:165], v[48:51]
	v_mfma_f32_16x16x32_bf16 v[36:39], v[206:209], v[170:173], v[36:39]
	v_mfma_f32_16x16x32_bf16 v[32:35], v[214:217], v[170:173], v[32:35]
	v_mfma_f32_16x16x32_bf16 v[20:23], v[206:209], v[178:181], v[20:23]
	v_mfma_f32_16x16x32_bf16 v[16:19], v[214:217], v[178:181], v[16:19]
	v_mfma_f32_16x16x32_bf16 v[4:7], v[206:209], v[186:189], v[4:7]
	v_mfma_f32_16x16x32_bf16 v[0:3], v[214:217], v[186:189], v[0:3]
	s_setprio 0
	s_add_i32 s51, 0, 0x18000
	v_add_u32_e32 v154, s51, v148
	s_barrier
	ds_read_b128 v[138:141], v154
	ds_read_b128 v[142:145], v154 offset:1024
	ds_read_b128 v[150:153], v154 offset:2048
	ds_read_b128 v[154:157], v154 offset:3072
	s_add_u32 s36, s36, 0x40000
	s_addc_u32 s37, s37, 0
	s_mov_b32 m0, s46
	ds_read_b128 v[158:161], v149 offset:32768
	ds_read_b128 v[162:165], v149 offset:33792
	ds_read_b128 v[166:169], v149 offset:34816
	ds_read_b128 v[170:173], v149 offset:35840
	ds_read_b128 v[174:177], v149 offset:36864
	ds_read_b128 v[178:181], v149 offset:37888
	ds_read_b128 v[182:185], v149 offset:38912
	ds_read_b128 v[186:189], v149 offset:39936
	global_load_lds_dwordx4 v128, s[36:37]
	s_mov_b32 m0, s47
	s_nop 0
	global_load_lds_dwordx4 v130, s[36:37]
	s_waitcnt lgkmcnt(8)
	s_barrier
	s_waitcnt lgkmcnt(0)
	s_setprio 1
	s_waitcnt lgkmcnt(0)
	v_mfma_f32_16x16x32_bf16 v[124:127], v[138:141], v[158:161], v[124:127]
	v_mfma_f32_16x16x32_bf16 v[120:123], v[150:153], v[158:161], v[120:123]
	v_mfma_f32_16x16x32_bf16 v[108:111], v[138:141], v[166:169], v[108:111]
	v_mfma_f32_16x16x32_bf16 v[104:107], v[150:153], v[166:169], v[104:107]
	v_mfma_f32_16x16x32_bf16 v[92:95], v[138:141], v[174:177], v[92:95]
	v_mfma_f32_16x16x32_bf16 v[88:91], v[150:153], v[174:177], v[88:91]
	v_mfma_f32_16x16x32_bf16 v[76:79], v[138:141], v[182:185], v[76:79]
	v_mfma_f32_16x16x32_bf16 v[72:75], v[150:153], v[182:185], v[72:75]
	v_mfma_f32_16x16x32_bf16 v[124:127], v[142:145], v[162:165], v[124:127]
	v_mfma_f32_16x16x32_bf16 v[120:123], v[154:157], v[162:165], v[120:123]
	v_mfma_f32_16x16x32_bf16 v[108:111], v[142:145], v[170:173], v[108:111]
	v_mfma_f32_16x16x32_bf16 v[104:107], v[154:157], v[170:173], v[104:107]
	v_mfma_f32_16x16x32_bf16 v[92:95], v[142:145], v[178:181], v[92:95]
	v_mfma_f32_16x16x32_bf16 v[88:91], v[154:157], v[178:181], v[88:91]
	v_mfma_f32_16x16x32_bf16 v[76:79], v[142:145], v[186:189], v[76:79]
	v_mfma_f32_16x16x32_bf16 v[72:75], v[154:157], v[186:189], v[72:75]
	s_setprio 0
	s_barrier
	s_add_i32 s36, 0, 0x1c000
	s_add_i32 s37, s51, s43
	v_add_u32_e32 v196, s36, v148
	s_add_u32 s100, s34, 0x80
	s_addc_u32 s101, s35, 0
	s_mov_b32 m0, s37
	ds_read_b128 v[198:201], v196
	ds_read_b128 v[206:209], v196 offset:1024
	ds_read_b128 v[210:213], v196 offset:2048
	ds_read_b128 v[214:217], v196 offset:3072
	global_load_lds_dwordx4 v192, s[100:101]
	s_add_i32 m0, s37, 0x2000
	s_nop 0
	global_load_lds_dwordx4 v132, s[100:101]
	s_barrier
	s_waitcnt lgkmcnt(0)
	s_setprio 1
	s_waitcnt lgkmcnt(0)
	v_mfma_f32_16x16x32_bf16 v[116:119], v[198:201], v[158:161], v[116:119]
	v_mfma_f32_16x16x32_bf16 v[112:115], v[210:213], v[158:161], v[112:115]
	v_mfma_f32_16x16x32_bf16 v[100:103], v[198:201], v[166:169], v[100:103]
	v_mfma_f32_16x16x32_bf16 v[96:99], v[210:213], v[166:169], v[96:99]
	v_mfma_f32_16x16x32_bf16 v[84:87], v[198:201], v[174:177], v[84:87]
	v_mfma_f32_16x16x32_bf16 v[80:83], v[210:213], v[174:177], v[80:83]
	v_mfma_f32_16x16x32_bf16 v[68:71], v[198:201], v[182:185], v[68:71]
	v_mfma_f32_16x16x32_bf16 v[64:67], v[210:213], v[182:185], v[64:67]
	v_mfma_f32_16x16x32_bf16 v[116:119], v[206:209], v[162:165], v[116:119]
	v_mfma_f32_16x16x32_bf16 v[112:115], v[214:217], v[162:165], v[112:115]
	v_mfma_f32_16x16x32_bf16 v[100:103], v[206:209], v[170:173], v[100:103]
	v_mfma_f32_16x16x32_bf16 v[96:99], v[214:217], v[170:173], v[96:99]
	v_mfma_f32_16x16x32_bf16 v[84:87], v[206:209], v[178:181], v[84:87]
	v_mfma_f32_16x16x32_bf16 v[80:83], v[214:217], v[178:181], v[80:83]
	v_mfma_f32_16x16x32_bf16 v[68:71], v[206:209], v[186:189], v[68:71]
	v_mfma_f32_16x16x32_bf16 v[64:67], v[214:217], v[186:189], v[64:67]
	s_setprio 0
	s_mov_b32 m0, s48
	s_barrier
	ds_read_b128 v[158:161], v149 offset:49152
	ds_read_b128 v[162:165], v149 offset:50176
	ds_read_b128 v[166:169], v149 offset:51200
	ds_read_b128 v[170:173], v149 offset:52224
	ds_read_b128 v[174:177], v149 offset:53248
	ds_read_b128 v[178:181], v149 offset:54272
	ds_read_b128 v[182:185], v149 offset:55296
	ds_read_b128 v[186:189], v149 offset:56320
	global_load_lds_dwordx4 v128, vcc
	s_mov_b32 m0, s49
	s_nop 0
	global_load_lds_dwordx4 v130, vcc
	s_barrier
	s_waitcnt lgkmcnt(0)
	s_setprio 1
	s_waitcnt lgkmcnt(0)
	v_mfma_f32_16x16x32_bf16 v[60:63], v[138:141], v[158:161], v[60:63]
	v_mfma_f32_16x16x32_bf16 v[56:59], v[150:153], v[158:161], v[56:59]
	v_mfma_f32_16x16x32_bf16 v[44:47], v[138:141], v[166:169], v[44:47]
	v_mfma_f32_16x16x32_bf16 v[40:43], v[150:153], v[166:169], v[40:43]
	v_mfma_f32_16x16x32_bf16 v[28:31], v[138:141], v[174:177], v[28:31]
	v_mfma_f32_16x16x32_bf16 v[24:27], v[150:153], v[174:177], v[24:27]
	v_mfma_f32_16x16x32_bf16 v[12:15], v[138:141], v[182:185], v[12:15]
	v_mfma_f32_16x16x32_bf16 v[8:11], v[150:153], v[182:185], v[8:11]
	v_mfma_f32_16x16x32_bf16 v[60:63], v[142:145], v[162:165], v[60:63]
	v_mfma_f32_16x16x32_bf16 v[56:59], v[154:157], v[162:165], v[56:59]
	v_mfma_f32_16x16x32_bf16 v[44:47], v[142:145], v[170:173], v[44:47]
	v_mfma_f32_16x16x32_bf16 v[40:43], v[154:157], v[170:173], v[40:43]
	v_mfma_f32_16x16x32_bf16 v[28:31], v[142:145], v[178:181], v[28:31]
	v_mfma_f32_16x16x32_bf16 v[24:27], v[154:157], v[178:181], v[24:27]
	v_mfma_f32_16x16x32_bf16 v[12:15], v[142:145], v[186:189], v[12:15]
	v_mfma_f32_16x16x32_bf16 v[8:11], v[154:157], v[186:189], v[8:11]
	s_setprio 0
	s_barrier
	s_add_u32 s34, s34, 0x40080
	s_addc_u32 s35, s35, 0
	s_add_i32 s36, s36, s43
	s_mov_b32 m0, s36
	s_nop 0
	global_load_lds_dwordx4 v192, s[34:35]
	s_add_i32 m0, s36, 0x2000
	s_nop 0
	global_load_lds_dwordx4 v132, s[34:35]
	s_waitcnt vmcnt(6)
	s_barrier
	s_setprio 1
	v_mfma_f32_16x16x32_bf16 v[52:55], v[198:201], v[158:161], v[52:55]
	v_mfma_f32_16x16x32_bf16 v[48:51], v[210:213], v[158:161], v[48:51]
	v_mfma_f32_16x16x32_bf16 v[36:39], v[198:201], v[166:169], v[36:39]
	v_mfma_f32_16x16x32_bf16 v[32:35], v[210:213], v[166:169], v[32:35]
	v_mfma_f32_16x16x32_bf16 v[20:23], v[198:201], v[174:177], v[20:23]
	v_mfma_f32_16x16x32_bf16 v[16:19], v[210:213], v[174:177], v[16:19]
	v_mfma_f32_16x16x32_bf16 v[4:7], v[198:201], v[182:185], v[4:7]
	v_mfma_f32_16x16x32_bf16 v[0:3], v[210:213], v[182:185], v[0:3]
	v_mfma_f32_16x16x32_bf16 v[52:55], v[206:209], v[162:165], v[52:55]
	v_mfma_f32_16x16x32_bf16 v[48:51], v[214:217], v[162:165], v[48:51]
	v_mfma_f32_16x16x32_bf16 v[36:39], v[206:209], v[170:173], v[36:39]
	v_mfma_f32_16x16x32_bf16 v[32:35], v[214:217], v[170:173], v[32:35]
	v_mfma_f32_16x16x32_bf16 v[20:23], v[206:209], v[178:181], v[20:23]
	v_mfma_f32_16x16x32_bf16 v[16:19], v[214:217], v[178:181], v[16:19]
	v_mfma_f32_16x16x32_bf16 v[4:7], v[206:209], v[186:189], v[4:7]
	v_mfma_f32_16x16x32_bf16 v[0:3], v[214:217], v[186:189], v[0:3]
	s_setprio 0
	s_add_i32 s33, s33, 2
	s_add_u32 s30, s30, 0x100
	s_addc_u32 s31, s31, 0
	s_add_u32 s19, s19, 0x100
	s_addc_u32 s25, s25, 0
	s_cmp_gt_u32 s33, 13
	s_barrier
	s_cbranch_scc0 .LBB0_2148
	v_mov_b32_e32 v138, v252
	s_lshl_b32 s1, s8, 8
	v_readfirstlane_b32 s0, v138
	s_ashr_i32 s7, s0, 2
	s_andn2_b32 s7, s7, 63
	s_add_i32 s7, s7, s1
	v_and_or_b32 v140, v138, 15, s7
	v_ashrrev_i32_e32 v141, 31, v140
	v_lshl_add_u64 v[142:143], v[140:141], 2, s[14:15]
	global_load_dword v139, v[142:143], off
	global_load_dword v153, v[142:143], off offset:64
	global_load_dword v152, v[142:143], off offset:128
	global_load_dword v151, v[142:143], off offset:192
	s_lshl_b32 s1, s6, 8
	s_lshr_b32 s0, s0, 1
	s_and_b32 s0, s0, 0x60
	v_lshrrev_b32_e32 v138, 1, v138
	s_or_b32 s0, s0, s1
	v_and_or_b32 v138, v138, 24, s0
	v_mad_i64_i32 v[154:155], s[0:1], v140, s55, 0
	v_cmp_gt_i32_e32 vcc, s55, v138
	s_waitcnt vmcnt(0)
	v_fmamk_f32 v139, v139, 0x3a800000, v194
	v_mul_f32_e32 v144, 0x4b800000, v139
	v_cmp_gt_f32_e64 s[6:7], s2, v139
	s_nop 1
	v_cndmask_b32_e64 v139, v139, v144, s[6:7]
	v_rsq_f32_e32 v144, v139
	v_ashrrev_i32_e32 v139, 31, v138
	v_mul_f32_e32 v145, 0x45800000, v144
	v_cndmask_b32_e64 v144, v144, v145, s[6:7]
	v_pk_mul_f32 v[126:127], v[126:127], v[144:145] op_sel_hi:[1,0]
	v_pk_mul_f32 v[124:125], v[124:125], v[144:145] op_sel_hi:[1,0]
	v_pk_mul_f32 v[146:147], v[122:123], v[144:145] op_sel_hi:[1,0]
	v_pk_mul_f32 v[120:121], v[120:121], v[144:145] op_sel_hi:[1,0]
	v_lshl_add_u64 v[122:123], v[154:155], 1, s[12:13]
	s_and_saveexec_b64 s[6:7], vcc
	s_cbranch_execz .LBB0_2151
	v_cvt_pk_bf16_f32 v150, v125, v127
	v_cvt_pk_bf16_f32 v145, v124, v126
	v_and_b32_e32 v154, 0xffff0000, v150
	v_lshlrev_b32_e32 v150, 16, v150
	v_or_b32_sdwa v155, v154, v145 dst_sel:DWORD dst_unused:UNUSED_PAD src0_sel:DWORD src1_sel:WORD_1
	v_or_b32_sdwa v154, v150, v145 dst_sel:DWORD dst_unused:UNUSED_PAD src0_sel:DWORD src1_sel:WORD_0
	v_cvt_pk_bf16_f32 v150, v121, v147
	v_cvt_pk_bf16_f32 v145, v120, v146
	v_and_b32_e32 v156, 0xffff0000, v150
	v_lshlrev_b32_e32 v150, 16, v150
	v_lshl_add_u64 v[158:159], v[138:139], 1, v[122:123]
	v_or_b32_sdwa v157, v156, v145 dst_sel:DWORD dst_unused:UNUSED_PAD src0_sel:DWORD src1_sel:WORD_1
	v_or_b32_sdwa v156, v150, v145 dst_sel:DWORD dst_unused:UNUSED_PAD src0_sel:DWORD src1_sel:WORD_0
	global_store_dwordx4 v[158:159], v[154:157], off

.LBB0_2292:
	s_add_u32 s8, s12, 0x100
	s_addc_u32 s9, s13, 0
	s_add_i32 s53, 0, 0x10000
	v_add_u32_e32 v140, s53, v196
	ds_read_b128 v[128:131], v140
	ds_read_b128 v[132:135], v140 offset:1024
	ds_read_b128 v[136:139], v140 offset:2048
	ds_read_b128 v[140:143], v140 offset:3072
	s_cmp_eq_u32 s52, 2
	s_cselect_b32 s15, s31, s9
	s_cselect_b32 s14, s30, s8
	s_cselect_b32 s11, s35, s51
	s_cselect_b32 s10, s34, s33
	s_add_i32 m0, s42, 0xc000
	ds_read_b128 v[144:147], v198
	ds_read_b128 v[148:151], v198 offset:1024
	ds_read_b128 v[152:155], v198 offset:2048
	ds_read_b128 v[156:159], v198 offset:3072
	ds_read_b128 v[160:163], v198 offset:4096
	ds_read_b128 v[164:167], v198 offset:5120
	ds_read_b128 v[168:171], v198 offset:6144
	ds_read_b128 v[172:175], v198 offset:7168
	global_load_lds_dwordx4 v190, s[12:13]
	s_add_i32 m0, s42, 0xe000
	s_nop 0
	global_load_lds_dwordx4 v206, s[12:13]
	s_waitcnt lgkmcnt(8)
	s_barrier
	s_waitcnt lgkmcnt(0)
	s_setprio 1
	s_waitcnt lgkmcnt(0)
	v_mfma_f32_16x16x32_bf16 v[124:127], v[128:131], v[144:147], v[124:127]
	v_mfma_f32_16x16x32_bf16 v[120:123], v[136:139], v[144:147], v[120:123]
	v_mfma_f32_16x16x32_bf16 v[108:111], v[128:131], v[152:155], v[108:111]
	v_mfma_f32_16x16x32_bf16 v[104:107], v[136:139], v[152:155], v[104:107]
	v_mfma_f32_16x16x32_bf16 v[92:95], v[128:131], v[160:163], v[92:95]
	v_mfma_f32_16x16x32_bf16 v[88:91], v[136:139], v[160:163], v[88:91]
	v_mfma_f32_16x16x32_bf16 v[76:79], v[128:131], v[168:171], v[76:79]
	v_mfma_f32_16x16x32_bf16 v[72:75], v[136:139], v[168:171], v[72:75]
	v_mfma_f32_16x16x32_bf16 v[124:127], v[132:135], v[148:151], v[124:127]
	v_mfma_f32_16x16x32_bf16 v[120:123], v[140:143], v[148:151], v[120:123]
	v_mfma_f32_16x16x32_bf16 v[108:111], v[132:135], v[156:159], v[108:111]
	v_mfma_f32_16x16x32_bf16 v[104:107], v[140:143], v[156:159], v[104:107]
	v_mfma_f32_16x16x32_bf16 v[92:95], v[132:135], v[164:167], v[92:95]
	v_mfma_f32_16x16x32_bf16 v[88:91], v[140:143], v[164:167], v[88:91]
	v_mfma_f32_16x16x32_bf16 v[76:79], v[132:135], v[172:175], v[76:79]
	v_mfma_f32_16x16x32_bf16 v[72:75], v[140:143], v[172:175], v[72:75]
	s_setprio 0
	s_barrier
	s_add_i32 s54, 0, 0x14000
	v_add_u32_e32 v184, s54, v196
	s_add_i32 s12, s53, s41
	ds_read_b128 v[176:179], v184
	ds_read_b128 v[180:183], v184 offset:1024
	ds_read_b128 v[208:211], v184 offset:2048
	ds_read_b128 v[212:215], v184 offset:3072
	s_mov_b32 m0, s12
	s_nop 0
	global_load_lds_dwordx4 v186, s[10:11]
	s_add_i32 m0, s12, 0x2000
	s_nop 0
	global_load_lds_dwordx4 v188, s[10:11]
	s_barrier
	s_waitcnt lgkmcnt(0)
	s_setprio 1
	s_waitcnt lgkmcnt(0)
	v_mfma_f32_16x16x32_bf16 v[116:119], v[176:179], v[144:147], v[116:119]
	v_mfma_f32_16x16x32_bf16 v[112:115], v[208:211], v[144:147], v[112:115]
	v_mfma_f32_16x16x32_bf16 v[100:103], v[176:179], v[152:155], v[100:103]
	v_mfma_f32_16x16x32_bf16 v[96:99], v[208:211], v[152:155], v[96:99]
	v_mfma_f32_16x16x32_bf16 v[84:87], v[176:179], v[160:163], v[84:87]
	v_mfma_f32_16x16x32_bf16 v[80:83], v[208:211], v[160:163], v[80:83]
	v_mfma_f32_16x16x32_bf16 v[68:71], v[176:179], v[168:171], v[68:71]
	v_mfma_f32_16x16x32_bf16 v[64:67], v[208:211], v[168:171], v[64:67]
	v_mfma_f32_16x16x32_bf16 v[116:119], v[180:183], v[148:151], v[116:119]
	v_mfma_f32_16x16x32_bf16 v[112:115], v[212:215], v[148:151], v[112:115]
	v_mfma_f32_16x16x32_bf16 v[100:103], v[180:183], v[156:159], v[100:103]
	v_mfma_f32_16x16x32_bf16 v[96:99], v[212:215], v[156:159], v[96:99]
	v_mfma_f32_16x16x32_bf16 v[84:87], v[180:183], v[164:167], v[84:87]
	v_mfma_f32_16x16x32_bf16 v[80:83], v[212:215], v[164:167], v[80:83]
	v_mfma_f32_16x16x32_bf16 v[68:71], v[180:183], v[172:175], v[68:71]
	v_mfma_f32_16x16x32_bf16 v[64:67], v[212:215], v[172:175], v[64:67]
	s_setprio 0
	s_mov_b32 m0, s42
	s_barrier
	ds_read_b128 v[144:147], v198 offset:16384
	ds_read_b128 v[148:151], v198 offset:17408
	ds_read_b128 v[152:155], v198 offset:18432
	ds_read_b128 v[156:159], v198 offset:19456
	ds_read_b128 v[160:163], v198 offset:20480
	ds_read_b128 v[164:167], v198 offset:21504
	ds_read_b128 v[168:171], v198 offset:22528
	ds_read_b128 v[172:175], v198 offset:23552
	global_load_lds_dwordx4 v186, s[14:15]
	s_mov_b32 m0, s43
	s_nop 0
	global_load_lds_dwordx4 v188, s[14:15]
	s_barrier
	s_waitcnt lgkmcnt(0)
	s_setprio 1
	s_waitcnt lgkmcnt(0)
	v_mfma_f32_16x16x32_bf16 v[60:63], v[128:131], v[144:147], v[60:63]
	v_mfma_f32_16x16x32_bf16 v[56:59], v[136:139], v[144:147], v[56:59]
	v_mfma_f32_16x16x32_bf16 v[44:47], v[128:131], v[152:155], v[44:47]
	v_mfma_f32_16x16x32_bf16 v[40:43], v[136:139], v[152:155], v[40:43]
	v_mfma_f32_16x16x32_bf16 v[28:31], v[128:131], v[160:163], v[28:31]
	v_mfma_f32_16x16x32_bf16 v[24:27], v[136:139], v[160:163], v[24:27]
	v_mfma_f32_16x16x32_bf16 v[12:15], v[128:131], v[168:171], v[12:15]
	v_mfma_f32_16x16x32_bf16 v[8:11], v[136:139], v[168:171], v[8:11]
	v_mfma_f32_16x16x32_bf16 v[60:63], v[132:135], v[148:151], v[60:63]
	v_mfma_f32_16x16x32_bf16 v[56:59], v[140:143], v[148:151], v[56:59]
	v_mfma_f32_16x16x32_bf16 v[44:47], v[132:135], v[156:159], v[44:47]
	v_mfma_f32_16x16x32_bf16 v[40:43], v[140:143], v[156:159], v[40:43]
	v_mfma_f32_16x16x32_bf16 v[28:31], v[132:135], v[164:167], v[28:31]
	v_mfma_f32_16x16x32_bf16 v[24:27], v[140:143], v[164:167], v[24:27]
	v_mfma_f32_16x16x32_bf16 v[12:15], v[132:135], v[172:175], v[12:15]
	v_mfma_f32_16x16x32_bf16 v[8:11], v[140:143], v[172:175], v[8:11]
	s_setprio 0
	s_barrier
	s_add_u32 s12, s10, 0x18000
	s_addc_u32 s13, s11, 0
	s_add_i32 s53, s54, s41
	s_mov_b32 m0, s53
	s_nop 0
	global_load_lds_dwordx4 v186, s[12:13]
	s_add_i32 m0, s53, 0x2000
	s_nop 0
	global_load_lds_dwordx4 v188, s[12:13]
	s_waitcnt vmcnt(6)
	s_barrier
	s_setprio 1
	v_mfma_f32_16x16x32_bf16 v[52:55], v[176:179], v[144:147], v[52:55]
	v_mfma_f32_16x16x32_bf16 v[48:51], v[208:211], v[144:147], v[48:51]
	v_mfma_f32_16x16x32_bf16 v[36:39], v[176:179], v[152:155], v[36:39]
	v_mfma_f32_16x16x32_bf16 v[32:35], v[208:211], v[152:155], v[32:35]
	v_mfma_f32_16x16x32_bf16 v[20:23], v[176:179], v[160:163], v[20:23]
	v_mfma_f32_16x16x32_bf16 v[16:19], v[208:211], v[160:163], v[16:19]
	v_mfma_f32_16x16x32_bf16 v[4:7], v[176:179], v[168:171], v[4:7]
	v_mfma_f32_16x16x32_bf16 v[0:3], v[208:211], v[168:171], v[0:3]
	v_mfma_f32_16x16x32_bf16 v[52:55], v[180:183], v[148:151], v[52:55]
	v_mfma_f32_16x16x32_bf16 v[48:51], v[212:215], v[148:151], v[48:51]
	v_mfma_f32_16x16x32_bf16 v[36:39], v[180:183], v[156:159], v[36:39]
	v_mfma_f32_16x16x32_bf16 v[32:35], v[212:215], v[156:159], v[32:35]
	v_mfma_f32_16x16x32_bf16 v[20:23], v[180:183], v[164:167], v[20:23]
	v_mfma_f32_16x16x32_bf16 v[16:19], v[212:215], v[164:167], v[16:19]
	v_mfma_f32_16x16x32_bf16 v[4:7], v[180:183], v[172:175], v[4:7]
	v_mfma_f32_16x16x32_bf16 v[0:3], v[212:215], v[172:175], v[0:3]
	s_setprio 0
	s_add_i32 s53, 0, 0x18000
	v_add_u32_e32 v140, s53, v196
	s_barrier
	ds_read_b128 v[128:131], v140
	ds_read_b128 v[132:135], v140 offset:1024
	ds_read_b128 v[136:139], v140 offset:2048
	ds_read_b128 v[140:143], v140 offset:3072
	s_add_u32 s12, s14, 0x18000
	s_addc_u32 s13, s15, 0
	s_mov_b32 m0, s44
	ds_read_b128 v[144:147], v198 offset:32768
	ds_read_b128 v[148:151], v198 offset:33792
	ds_read_b128 v[152:155], v198 offset:34816
	ds_read_b128 v[156:159], v198 offset:35840
	ds_read_b128 v[160:163], v198 offset:36864
	ds_read_b128 v[164:167], v198 offset:37888
	ds_read_b128 v[168:171], v198 offset:38912
	ds_read_b128 v[172:175], v198 offset:39936
	global_load_lds_dwordx4 v186, s[12:13]
	s_mov_b32 m0, s45
	s_nop 0
	global_load_lds_dwordx4 v188, s[12:13]
	s_waitcnt lgkmcnt(8)
	s_barrier
	s_waitcnt lgkmcnt(0)
	s_setprio 1
	s_waitcnt lgkmcnt(0)
	v_mfma_f32_16x16x32_bf16 v[124:127], v[128:131], v[144:147], v[124:127]
	v_mfma_f32_16x16x32_bf16 v[120:123], v[136:139], v[144:147], v[120:123]
	v_mfma_f32_16x16x32_bf16 v[108:111], v[128:131], v[152:155], v[108:111]
	v_mfma_f32_16x16x32_bf16 v[104:107], v[136:139], v[152:155], v[104:107]
	v_mfma_f32_16x16x32_bf16 v[92:95], v[128:131], v[160:163], v[92:95]
	v_mfma_f32_16x16x32_bf16 v[88:91], v[136:139], v[160:163], v[88:91]
	v_mfma_f32_16x16x32_bf16 v[76:79], v[128:131], v[168:171], v[76:79]
	v_mfma_f32_16x16x32_bf16 v[72:75], v[136:139], v[168:171], v[72:75]
	v_mfma_f32_16x16x32_bf16 v[124:127], v[132:135], v[148:151], v[124:127]
	v_mfma_f32_16x16x32_bf16 v[120:123], v[140:143], v[148:151], v[120:123]
	v_mfma_f32_16x16x32_bf16 v[108:111], v[132:135], v[156:159], v[108:111]
	v_mfma_f32_16x16x32_bf16 v[104:107], v[140:143], v[156:159], v[104:107]
	v_mfma_f32_16x16x32_bf16 v[92:95], v[132:135], v[164:167], v[92:95]
	v_mfma_f32_16x16x32_bf16 v[88:91], v[140:143], v[164:167], v[88:91]
	v_mfma_f32_16x16x32_bf16 v[76:79], v[132:135], v[172:175], v[76:79]
	v_mfma_f32_16x16x32_bf16 v[72:75], v[140:143], v[172:175], v[72:75]
	s_setprio 0
	s_barrier
	s_add_i32 s12, 0, 0x1c000
	s_add_i32 s13, s53, s41
	v_add_u32_e32 v192, s12, v196
	s_add_u32 s100, s10, 0x80
	s_addc_u32 s101, s11, 0
	s_mov_b32 m0, s13
	ds_read_b128 v[176:179], v192
	ds_read_b128 v[180:183], v192 offset:1024
	ds_read_b128 v[208:211], v192 offset:2048
	ds_read_b128 v[212:215], v192 offset:3072
	global_load_lds_dwordx4 v186, s[100:101]
	s_add_i32 m0, s13, 0x2000
	s_nop 0
	global_load_lds_dwordx4 v188, s[100:101]
	s_barrier
	s_waitcnt lgkmcnt(0)
	s_setprio 1
	s_waitcnt lgkmcnt(0)
	v_mfma_f32_16x16x32_bf16 v[116:119], v[176:179], v[144:147], v[116:119]
	v_mfma_f32_16x16x32_bf16 v[112:115], v[208:211], v[144:147], v[112:115]
	v_mfma_f32_16x16x32_bf16 v[100:103], v[176:179], v[152:155], v[100:103]
	v_mfma_f32_16x16x32_bf16 v[96:99], v[208:211], v[152:155], v[96:99]
	v_mfma_f32_16x16x32_bf16 v[84:87], v[176:179], v[160:163], v[84:87]
	v_mfma_f32_16x16x32_bf16 v[80:83], v[208:211], v[160:163], v[80:83]
	v_mfma_f32_16x16x32_bf16 v[68:71], v[176:179], v[168:171], v[68:71]
	v_mfma_f32_16x16x32_bf16 v[64:67], v[208:211], v[168:171], v[64:67]
	v_mfma_f32_16x16x32_bf16 v[116:119], v[180:183], v[148:151], v[116:119]
	v_mfma_f32_16x16x32_bf16 v[112:115], v[212:215], v[148:151], v[112:115]
	v_mfma_f32_16x16x32_bf16 v[100:103], v[180:183], v[156:159], v[100:103]
	v_mfma_f32_16x16x32_bf16 v[96:99], v[212:215], v[156:159], v[96:99]
	v_mfma_f32_16x16x32_bf16 v[84:87], v[180:183], v[164:167], v[84:87]
	v_mfma_f32_16x16x32_bf16 v[80:83], v[212:215], v[164:167], v[80:83]
	v_mfma_f32_16x16x32_bf16 v[68:71], v[180:183], v[172:175], v[68:71]
	v_mfma_f32_16x16x32_bf16 v[64:67], v[212:215], v[172:175], v[64:67]
	s_setprio 0
	s_mov_b32 m0, s46
	s_add_u32 s100, s14, 0x80
	s_addc_u32 s101, s15, 0
	s_barrier
	ds_read_b128 v[144:147], v198 offset:49152
	ds_read_b128 v[148:151], v198 offset:50176
	ds_read_b128 v[152:155], v198 offset:51200
	ds_read_b128 v[156:159], v198 offset:52224
	ds_read_b128 v[160:163], v198 offset:53248
	ds_read_b128 v[164:167], v198 offset:54272
	ds_read_b128 v[168:171], v198 offset:55296
	ds_read_b128 v[172:175], v198 offset:56320
	global_load_lds_dwordx4 v186, s[100:101]
	s_mov_b32 m0, s47
	s_nop 0
	global_load_lds_dwordx4 v188, s[100:101]
	s_barrier
	s_waitcnt lgkmcnt(0)
	s_setprio 1
	s_waitcnt lgkmcnt(0)
	v_mfma_f32_16x16x32_bf16 v[60:63], v[128:131], v[144:147], v[60:63]
	v_mfma_f32_16x16x32_bf16 v[56:59], v[136:139], v[144:147], v[56:59]
	v_mfma_f32_16x16x32_bf16 v[44:47], v[128:131], v[152:155], v[44:47]
	v_mfma_f32_16x16x32_bf16 v[40:43], v[136:139], v[152:155], v[40:43]
	v_mfma_f32_16x16x32_bf16 v[28:31], v[128:131], v[160:163], v[28:31]
	v_mfma_f32_16x16x32_bf16 v[24:27], v[136:139], v[160:163], v[24:27]
	v_mfma_f32_16x16x32_bf16 v[12:15], v[128:131], v[168:171], v[12:15]
	v_mfma_f32_16x16x32_bf16 v[8:11], v[136:139], v[168:171], v[8:11]
	v_mfma_f32_16x16x32_bf16 v[60:63], v[132:135], v[148:151], v[60:63]
	v_mfma_f32_16x16x32_bf16 v[56:59], v[140:143], v[148:151], v[56:59]
	v_mfma_f32_16x16x32_bf16 v[44:47], v[132:135], v[156:159], v[44:47]
	v_mfma_f32_16x16x32_bf16 v[40:43], v[140:143], v[156:159], v[40:43]
	v_mfma_f32_16x16x32_bf16 v[28:31], v[132:135], v[164:167], v[28:31]
	v_mfma_f32_16x16x32_bf16 v[24:27], v[140:143], v[164:167], v[24:27]
	v_mfma_f32_16x16x32_bf16 v[12:15], v[132:135], v[172:175], v[12:15]
	v_mfma_f32_16x16x32_bf16 v[8:11], v[140:143], v[172:175], v[8:11]
	s_setprio 0
	s_barrier
	s_add_u32 s10, s10, 0x18080
	s_addc_u32 s11, s11, 0
	s_add_i32 s12, s12, s41
	s_mov_b32 m0, s12
	s_nop 0
	global_load_lds_dwordx4 v186, s[10:11]
	s_add_i32 m0, s12, 0x2000
	s_nop 0
	global_load_lds_dwordx4 v188, s[10:11]
	s_waitcnt vmcnt(6)
	s_barrier
	s_setprio 1
	v_mfma_f32_16x16x32_bf16 v[52:55], v[176:179], v[144:147], v[52:55]
	v_mfma_f32_16x16x32_bf16 v[48:51], v[208:211], v[144:147], v[48:51]
	v_mfma_f32_16x16x32_bf16 v[36:39], v[176:179], v[152:155], v[36:39]
	v_mfma_f32_16x16x32_bf16 v[32:35], v[208:211], v[152:155], v[32:35]
	v_mfma_f32_16x16x32_bf16 v[20:23], v[176:179], v[160:163], v[20:23]
	v_mfma_f32_16x16x32_bf16 v[16:19], v[208:211], v[160:163], v[16:19]
	v_mfma_f32_16x16x32_bf16 v[4:7], v[176:179], v[168:171], v[4:7]
	v_mfma_f32_16x16x32_bf16 v[0:3], v[208:211], v[168:171], v[0:3]
	v_mfma_f32_16x16x32_bf16 v[52:55], v[180:183], v[148:151], v[52:55]
	v_mfma_f32_16x16x32_bf16 v[48:51], v[212:215], v[148:151], v[48:51]
	v_mfma_f32_16x16x32_bf16 v[36:39], v[180:183], v[156:159], v[36:39]
	v_mfma_f32_16x16x32_bf16 v[32:35], v[212:215], v[156:159], v[32:35]
	v_mfma_f32_16x16x32_bf16 v[20:23], v[180:183], v[164:167], v[20:23]
	v_mfma_f32_16x16x32_bf16 v[16:19], v[212:215], v[164:167], v[16:19]
	v_mfma_f32_16x16x32_bf16 v[4:7], v[180:183], v[172:175], v[4:7]
	v_mfma_f32_16x16x32_bf16 v[0:3], v[212:215], v[172:175], v[0:3]
	s_setprio 0
	s_add_i32 s52, s52, 2
	s_add_u32 s33, s33, 0x100
	s_addc_u32 s51, s51, 0
	s_cmp_gt_u32 s52, 3
	s_mov_b64 s[12:13], s[8:9]
	s_barrier
	s_cbranch_scc0 .LBB0_2292
	v_mov_b32_e32 v128, v252
	s_lshl_b32 s1, s1, 8
	v_readfirstlane_b32 s8, v128
	s_ashr_i32 s9, s8, 2
	s_andn2_b32 s9, s9, 63
	s_add_i32 s9, s9, s1
	v_and_or_b32 v208, v128, 15, s9
	v_ashrrev_i32_e32 v209, 31, v208
	v_lshl_add_u64 v[210:211], v[208:209], 2, s[26:27]
	global_load_dword v225, v[210:211], off
	s_lshr_b32 s1, s8, 1
	s_and_b32 s1, s1, 0x60
	s_lshl_b32 s0, s0, 8
	v_lshrrev_b32_e32 v128, 2, v128
	s_or_b32 s0, s1, s0
	s_movk_i32 s1, 0x1fcf
	v_and_b32_e32 v226, 12, v128
	v_and_or_b32 v128, v208, s1, 16
	s_movk_i32 s1, 0x4000
	v_cmp_gt_i32_e32 vcc, s1, v208
	s_mul_hi_i32 s1, s0, 0x2aaaaaab
	s_lshr_b32 s8, s1, 31
	s_lshr_b32 s1, s1, 4
	s_add_i32 s1, s1, s8
	s_mulk_i32 s1, 0x60
	v_add_u32_e32 v129, 0x7ffc000, v208
	s_sub_i32 s1, s0, s1
	v_lshlrev_b32_e32 v199, 1, v226
	v_cndmask_b32_e32 v128, v129, v128, vcc
	s_cmp_eq_u32 s1, 64
	v_lshl_or_b32 v192, v128, 5, v199
	s_cselect_b64 s[10:11], -1, 0
	v_lshl_add_u64 v[128:129], v[192:193], 2, s[28:29]
	v_mov_b32_e32 v160, 0
	s_and_b64 vcc, exec, s[10:11]
	v_mov_b32_e32 v178, 0
	v_mov_b32_e32 v218, 0
	v_mov_b32_e32 v179, 0
	v_mov_b32_e32 v219, 0
	v_mov_b32_e32 v182, 0
	v_mov_b32_e32 v220, 0
	v_mov_b32_e32 v183, 0
	v_mov_b32_e32 v221, 0
	s_cbranch_vccz .LBB0_2295
	global_load_dwordx4 v[178:181], v[128:129], off
	global_load_dwordx4 v[182:185], v[128:129], off offset:16
	s_waitcnt vmcnt(0)
	v_mov_b32_e32 v218, v179
	v_mov_b32_e32 v179, v180
	v_mov_b32_e32 v219, v181
	v_mov_b32_e32 v220, v183
	v_mov_b32_e32 v183, v184
	v_mov_b32_e32 v221, v185

.LBB0_2484:
	s_add_u32 s34, s30, 0xfffe0080
	s_addc_u32 s35, s31, -1
	s_add_i32 s53, 0, 0x10000
	v_add_u32_e32 v140, s53, v196
	ds_read_b128 v[128:131], v140
	ds_read_b128 v[132:135], v140 offset:1024
	ds_read_b128 v[136:139], v140 offset:2048
	ds_read_b128 v[140:143], v140 offset:3072
	s_cmp_eq_u32 s52, 4
	s_cselect_b32 s37, s0, s35
	s_cselect_b32 s36, s1, s34
	s_cselect_b32 s35, s15, s33
	s_cselect_b32 s34, s21, s27
	s_add_i32 m0, s29, 0xc000
	ds_read_b128 v[144:147], v198
	ds_read_b128 v[148:151], v198 offset:1024
	ds_read_b128 v[152:155], v198 offset:2048
	ds_read_b128 v[156:159], v198 offset:3072
	ds_read_b128 v[160:163], v198 offset:4096
	ds_read_b128 v[164:167], v198 offset:5120
	ds_read_b128 v[168:171], v198 offset:6144
	ds_read_b128 v[172:175], v198 offset:7168
	global_load_lds_dwordx4 v212, s[30:31]
	s_add_i32 m0, s29, 0xe000
	s_nop 0
	global_load_lds_dwordx4 v214, s[30:31]
	s_waitcnt lgkmcnt(8)
	s_barrier
	s_waitcnt lgkmcnt(0)
	s_setprio 1
	s_waitcnt lgkmcnt(0)
	v_mfma_f32_16x16x32_bf16 v[124:127], v[128:131], v[144:147], v[124:127]
	v_mfma_f32_16x16x32_bf16 v[120:123], v[136:139], v[144:147], v[120:123]
	v_mfma_f32_16x16x32_bf16 v[108:111], v[128:131], v[152:155], v[108:111]
	v_mfma_f32_16x16x32_bf16 v[104:107], v[136:139], v[152:155], v[104:107]
	v_mfma_f32_16x16x32_bf16 v[92:95], v[128:131], v[160:163], v[92:95]
	v_mfma_f32_16x16x32_bf16 v[88:91], v[136:139], v[160:163], v[88:91]
	v_mfma_f32_16x16x32_bf16 v[76:79], v[128:131], v[168:171], v[76:79]
	v_mfma_f32_16x16x32_bf16 v[72:75], v[136:139], v[168:171], v[72:75]
	v_mfma_f32_16x16x32_bf16 v[124:127], v[132:135], v[148:151], v[124:127]
	v_mfma_f32_16x16x32_bf16 v[120:123], v[140:143], v[148:151], v[120:123]
	v_mfma_f32_16x16x32_bf16 v[108:111], v[132:135], v[156:159], v[108:111]
	v_mfma_f32_16x16x32_bf16 v[104:107], v[140:143], v[156:159], v[104:107]
	v_mfma_f32_16x16x32_bf16 v[92:95], v[132:135], v[164:167], v[92:95]
	v_mfma_f32_16x16x32_bf16 v[88:91], v[140:143], v[164:167], v[88:91]
	v_mfma_f32_16x16x32_bf16 v[76:79], v[132:135], v[172:175], v[76:79]
	v_mfma_f32_16x16x32_bf16 v[72:75], v[140:143], v[172:175], v[72:75]
	s_setprio 0
	s_barrier
	s_add_i32 s56, 0, 0x14000
	s_add_i32 s53, s53, s45
	v_add_u32_e32 v188, s56, v196
	s_mov_b32 m0, s53
	ds_read_b128 v[176:179], v188
	ds_read_b128 v[180:183], v188 offset:1024
	ds_read_b128 v[184:187], v188 offset:2048
	ds_read_b128 v[188:191], v188 offset:3072
	global_load_lds_dwordx4 v192, s[34:35]
	s_add_i32 m0, s53, 0x2000
	s_nop 0
	global_load_lds_dwordx4 v210, s[34:35]
	s_barrier
	s_waitcnt lgkmcnt(0)
	s_setprio 1
	s_waitcnt lgkmcnt(0)
	v_mfma_f32_16x16x32_bf16 v[116:119], v[176:179], v[144:147], v[116:119]
	v_mfma_f32_16x16x32_bf16 v[112:115], v[184:187], v[144:147], v[112:115]
	v_mfma_f32_16x16x32_bf16 v[100:103], v[176:179], v[152:155], v[100:103]
	v_mfma_f32_16x16x32_bf16 v[96:99], v[184:187], v[152:155], v[96:99]
	v_mfma_f32_16x16x32_bf16 v[84:87], v[176:179], v[160:163], v[84:87]
	v_mfma_f32_16x16x32_bf16 v[80:83], v[184:187], v[160:163], v[80:83]
	v_mfma_f32_16x16x32_bf16 v[68:71], v[176:179], v[168:171], v[68:71]
	v_mfma_f32_16x16x32_bf16 v[64:67], v[184:187], v[168:171], v[64:67]
	v_mfma_f32_16x16x32_bf16 v[116:119], v[180:183], v[148:151], v[116:119]
	v_mfma_f32_16x16x32_bf16 v[112:115], v[188:191], v[148:151], v[112:115]
	v_mfma_f32_16x16x32_bf16 v[100:103], v[180:183], v[156:159], v[100:103]
	v_mfma_f32_16x16x32_bf16 v[96:99], v[188:191], v[156:159], v[96:99]
	v_mfma_f32_16x16x32_bf16 v[84:87], v[180:183], v[164:167], v[84:87]
	v_mfma_f32_16x16x32_bf16 v[80:83], v[188:191], v[164:167], v[80:83]
	v_mfma_f32_16x16x32_bf16 v[68:71], v[180:183], v[172:175], v[68:71]
	v_mfma_f32_16x16x32_bf16 v[64:67], v[188:191], v[172:175], v[64:67]
	s_setprio 0
	s_mov_b32 m0, s29
	s_add_u32 vcc_lo, s36, 0x80
	s_addc_u32 vcc_hi, s37, 0
	s_barrier
	ds_read_b128 v[144:147], v198 offset:16384
	ds_read_b128 v[148:151], v198 offset:17408
	ds_read_b128 v[152:155], v198 offset:18432
	ds_read_b128 v[156:159], v198 offset:19456
	ds_read_b128 v[160:163], v198 offset:20480
	ds_read_b128 v[164:167], v198 offset:21504
	ds_read_b128 v[168:171], v198 offset:22528
	ds_read_b128 v[172:175], v198 offset:23552
	global_load_lds_dwordx4 v206, s[36:37]
	s_mov_b32 m0, s46
	s_nop 0
	global_load_lds_dwordx4 v208, s[36:37]
	s_barrier
	s_waitcnt lgkmcnt(0)
	s_setprio 1
	s_waitcnt lgkmcnt(0)
	v_mfma_f32_16x16x32_bf16 v[60:63], v[128:131], v[144:147], v[60:63]
	v_mfma_f32_16x16x32_bf16 v[56:59], v[136:139], v[144:147], v[56:59]
	v_mfma_f32_16x16x32_bf16 v[44:47], v[128:131], v[152:155], v[44:47]
	v_mfma_f32_16x16x32_bf16 v[40:43], v[136:139], v[152:155], v[40:43]
	v_mfma_f32_16x16x32_bf16 v[28:31], v[128:131], v[160:163], v[28:31]
	v_mfma_f32_16x16x32_bf16 v[24:27], v[136:139], v[160:163], v[24:27]
	v_mfma_f32_16x16x32_bf16 v[12:15], v[128:131], v[168:171], v[12:15]
	v_mfma_f32_16x16x32_bf16 v[8:11], v[136:139], v[168:171], v[8:11]
	v_mfma_f32_16x16x32_bf16 v[60:63], v[132:135], v[148:151], v[60:63]
	v_mfma_f32_16x16x32_bf16 v[56:59], v[140:143], v[148:151], v[56:59]
	v_mfma_f32_16x16x32_bf16 v[44:47], v[132:135], v[156:159], v[44:47]
	v_mfma_f32_16x16x32_bf16 v[40:43], v[140:143], v[156:159], v[40:43]
	v_mfma_f32_16x16x32_bf16 v[28:31], v[132:135], v[164:167], v[28:31]
	v_mfma_f32_16x16x32_bf16 v[24:27], v[140:143], v[164:167], v[24:27]
	v_mfma_f32_16x16x32_bf16 v[12:15], v[132:135], v[172:175], v[12:15]
	v_mfma_f32_16x16x32_bf16 v[8:11], v[140:143], v[172:175], v[8:11]
	s_setprio 0
	s_barrier
	s_add_u32 s54, s34, 0x20000
	s_addc_u32 s55, s35, 0
	s_add_i32 s53, s56, s45
	s_mov_b32 m0, s53
	s_nop 0
	global_load_lds_dwordx4 v192, s[54:55]
	s_add_i32 m0, s53, 0x2000
	s_nop 0
	global_load_lds_dwordx4 v210, s[54:55]
	s_waitcnt vmcnt(6)
	s_barrier
	s_setprio 1
	v_mfma_f32_16x16x32_bf16 v[52:55], v[176:179], v[144:147], v[52:55]
	v_mfma_f32_16x16x32_bf16 v[48:51], v[184:187], v[144:147], v[48:51]
	v_mfma_f32_16x16x32_bf16 v[36:39], v[176:179], v[152:155], v[36:39]
	v_mfma_f32_16x16x32_bf16 v[32:35], v[184:187], v[152:155], v[32:35]
	v_mfma_f32_16x16x32_bf16 v[20:23], v[176:179], v[160:163], v[20:23]
	v_mfma_f32_16x16x32_bf16 v[16:19], v[184:187], v[160:163], v[16:19]
	v_mfma_f32_16x16x32_bf16 v[4:7], v[176:179], v[168:171], v[4:7]
	v_mfma_f32_16x16x32_bf16 v[0:3], v[184:187], v[168:171], v[0:3]
	v_mfma_f32_16x16x32_bf16 v[52:55], v[180:183], v[148:151], v[52:55]
	v_mfma_f32_16x16x32_bf16 v[48:51], v[188:191], v[148:151], v[48:51]
	v_mfma_f32_16x16x32_bf16 v[36:39], v[180:183], v[156:159], v[36:39]
	v_mfma_f32_16x16x32_bf16 v[32:35], v[188:191], v[156:159], v[32:35]
	v_mfma_f32_16x16x32_bf16 v[20:23], v[180:183], v[164:167], v[20:23]
	v_mfma_f32_16x16x32_bf16 v[16:19], v[188:191], v[164:167], v[16:19]
	v_mfma_f32_16x16x32_bf16 v[4:7], v[180:183], v[172:175], v[4:7]
	v_mfma_f32_16x16x32_bf16 v[0:3], v[188:191], v[172:175], v[0:3]
	s_setprio 0
	s_add_i32 s53, 0, 0x18000
	v_add_u32_e32 v140, s53, v196
	s_barrier
	ds_read_b128 v[128:131], v140
	ds_read_b128 v[132:135], v140 offset:1024
	ds_read_b128 v[136:139], v140 offset:2048
	ds_read_b128 v[140:143], v140 offset:3072
	s_add_u32 s36, s36, 0x20000
	s_addc_u32 s37, s37, 0
	s_mov_b32 m0, s47
	ds_read_b128 v[144:147], v198 offset:32768
	ds_read_b128 v[148:151], v198 offset:33792
	ds_read_b128 v[152:155], v198 offset:34816
	ds_read_b128 v[156:159], v198 offset:35840
	ds_read_b128 v[160:163], v198 offset:36864
	ds_read_b128 v[164:167], v198 offset:37888
	ds_read_b128 v[168:171], v198 offset:38912
	ds_read_b128 v[172:175], v198 offset:39936
	global_load_lds_dwordx4 v206, s[36:37]
	s_mov_b32 m0, s48
	s_nop 0
	global_load_lds_dwordx4 v208, s[36:37]
	s_waitcnt lgkmcnt(8)
	s_barrier
	s_waitcnt lgkmcnt(0)
	s_setprio 1
	s_waitcnt lgkmcnt(0)
	v_mfma_f32_16x16x32_bf16 v[124:127], v[128:131], v[144:147], v[124:127]
	v_mfma_f32_16x16x32_bf16 v[120:123], v[136:139], v[144:147], v[120:123]
	v_mfma_f32_16x16x32_bf16 v[108:111], v[128:131], v[152:155], v[108:111]
	v_mfma_f32_16x16x32_bf16 v[104:107], v[136:139], v[152:155], v[104:107]
	v_mfma_f32_16x16x32_bf16 v[92:95], v[128:131], v[160:163], v[92:95]
	v_mfma_f32_16x16x32_bf16 v[88:91], v[136:139], v[160:163], v[88:91]
	v_mfma_f32_16x16x32_bf16 v[76:79], v[128:131], v[168:171], v[76:79]
	v_mfma_f32_16x16x32_bf16 v[72:75], v[136:139], v[168:171], v[72:75]
	v_mfma_f32_16x16x32_bf16 v[124:127], v[132:135], v[148:151], v[124:127]
	v_mfma_f32_16x16x32_bf16 v[120:123], v[140:143], v[148:151], v[120:123]
	v_mfma_f32_16x16x32_bf16 v[108:111], v[132:135], v[156:159], v[108:111]
	v_mfma_f32_16x16x32_bf16 v[104:107], v[140:143], v[156:159], v[104:107]
	v_mfma_f32_16x16x32_bf16 v[92:95], v[132:135], v[164:167], v[92:95]
	v_mfma_f32_16x16x32_bf16 v[88:91], v[140:143], v[164:167], v[88:91]
	v_mfma_f32_16x16x32_bf16 v[76:79], v[132:135], v[172:175], v[76:79]
	v_mfma_f32_16x16x32_bf16 v[72:75], v[140:143], v[172:175], v[72:75]
	s_setprio 0
	s_barrier
	s_add_i32 s36, 0, 0x1c000
	s_add_i32 s37, s53, s45
	v_add_u32_e32 v188, s36, v196
	s_add_u32 s100, s34, 0x80
	s_addc_u32 s101, s35, 0
	s_mov_b32 m0, s37
	ds_read_b128 v[176:179], v188
	ds_read_b128 v[180:183], v188 offset:1024
	ds_read_b128 v[184:187], v188 offset:2048
	ds_read_b128 v[188:191], v188 offset:3072
	global_load_lds_dwordx4 v192, s[100:101]
	s_add_i32 m0, s37, 0x2000
	s_nop 0
	global_load_lds_dwordx4 v210, s[100:101]
	s_barrier
	s_waitcnt lgkmcnt(0)
	s_setprio 1
	s_waitcnt lgkmcnt(0)
	v_mfma_f32_16x16x32_bf16 v[116:119], v[176:179], v[144:147], v[116:119]
	v_mfma_f32_16x16x32_bf16 v[112:115], v[184:187], v[144:147], v[112:115]
	v_mfma_f32_16x16x32_bf16 v[100:103], v[176:179], v[152:155], v[100:103]
	v_mfma_f32_16x16x32_bf16 v[96:99], v[184:187], v[152:155], v[96:99]
	v_mfma_f32_16x16x32_bf16 v[84:87], v[176:179], v[160:163], v[84:87]
	v_mfma_f32_16x16x32_bf16 v[80:83], v[184:187], v[160:163], v[80:83]
	v_mfma_f32_16x16x32_bf16 v[68:71], v[176:179], v[168:171], v[68:71]
	v_mfma_f32_16x16x32_bf16 v[64:67], v[184:187], v[168:171], v[64:67]
	v_mfma_f32_16x16x32_bf16 v[116:119], v[180:183], v[148:151], v[116:119]
	v_mfma_f32_16x16x32_bf16 v[112:115], v[188:191], v[148:151], v[112:115]
	v_mfma_f32_16x16x32_bf16 v[100:103], v[180:183], v[156:159], v[100:103]
	v_mfma_f32_16x16x32_bf16 v[96:99], v[188:191], v[156:159], v[96:99]
	v_mfma_f32_16x16x32_bf16 v[84:87], v[180:183], v[164:167], v[84:87]
	v_mfma_f32_16x16x32_bf16 v[80:83], v[188:191], v[164:167], v[80:83]
	v_mfma_f32_16x16x32_bf16 v[68:71], v[180:183], v[172:175], v[68:71]
	v_mfma_f32_16x16x32_bf16 v[64:67], v[188:191], v[172:175], v[64:67]
	s_setprio 0
	s_mov_b32 m0, s49
	s_barrier
	ds_read_b128 v[144:147], v198 offset:49152
	ds_read_b128 v[148:151], v198 offset:50176
	ds_read_b128 v[152:155], v198 offset:51200
	ds_read_b128 v[156:159], v198 offset:52224
	ds_read_b128 v[160:163], v198 offset:53248
	ds_read_b128 v[164:167], v198 offset:54272
	ds_read_b128 v[168:171], v198 offset:55296
	ds_read_b128 v[172:175], v198 offset:56320
	global_load_lds_dwordx4 v206, vcc
	s_mov_b32 m0, s50
	s_nop 0
	global_load_lds_dwordx4 v208, vcc
	s_barrier
	s_waitcnt lgkmcnt(0)
	s_setprio 1
	s_waitcnt lgkmcnt(0)
	v_mfma_f32_16x16x32_bf16 v[60:63], v[128:131], v[144:147], v[60:63]
	v_mfma_f32_16x16x32_bf16 v[56:59], v[136:139], v[144:147], v[56:59]
	v_mfma_f32_16x16x32_bf16 v[44:47], v[128:131], v[152:155], v[44:47]
	v_mfma_f32_16x16x32_bf16 v[40:43], v[136:139], v[152:155], v[40:43]
	v_mfma_f32_16x16x32_bf16 v[28:31], v[128:131], v[160:163], v[28:31]
	v_mfma_f32_16x16x32_bf16 v[24:27], v[136:139], v[160:163], v[24:27]
	v_mfma_f32_16x16x32_bf16 v[12:15], v[128:131], v[168:171], v[12:15]
	v_mfma_f32_16x16x32_bf16 v[8:11], v[136:139], v[168:171], v[8:11]
	v_mfma_f32_16x16x32_bf16 v[60:63], v[132:135], v[148:151], v[60:63]
	v_mfma_f32_16x16x32_bf16 v[56:59], v[140:143], v[148:151], v[56:59]
	v_mfma_f32_16x16x32_bf16 v[44:47], v[132:135], v[156:159], v[44:47]
	v_mfma_f32_16x16x32_bf16 v[40:43], v[140:143], v[156:159], v[40:43]
	v_mfma_f32_16x16x32_bf16 v[28:31], v[132:135], v[164:167], v[28:31]
	v_mfma_f32_16x16x32_bf16 v[24:27], v[140:143], v[164:167], v[24:27]
	v_mfma_f32_16x16x32_bf16 v[12:15], v[132:135], v[172:175], v[12:15]
	v_mfma_f32_16x16x32_bf16 v[8:11], v[140:143], v[172:175], v[8:11]
	s_setprio 0
	s_barrier
	s_add_u32 s34, s34, 0x20080
	s_addc_u32 s35, s35, 0
	s_add_i32 s36, s36, s45
	s_mov_b32 m0, s36
	s_nop 0
	global_load_lds_dwordx4 v192, s[34:35]
	s_add_i32 m0, s36, 0x2000
	s_nop 0
	global_load_lds_dwordx4 v210, s[34:35]
	s_waitcnt vmcnt(6)
	s_barrier
	s_setprio 1
	v_mfma_f32_16x16x32_bf16 v[52:55], v[176:179], v[144:147], v[52:55]
	v_mfma_f32_16x16x32_bf16 v[48:51], v[184:187], v[144:147], v[48:51]
	v_mfma_f32_16x16x32_bf16 v[36:39], v[176:179], v[152:155], v[36:39]
	v_mfma_f32_16x16x32_bf16 v[32:35], v[184:187], v[152:155], v[32:35]
	v_mfma_f32_16x16x32_bf16 v[20:23], v[176:179], v[160:163], v[20:23]
	v_mfma_f32_16x16x32_bf16 v[16:19], v[184:187], v[160:163], v[16:19]
	v_mfma_f32_16x16x32_bf16 v[4:7], v[176:179], v[168:171], v[4:7]
	v_mfma_f32_16x16x32_bf16 v[0:3], v[184:187], v[168:171], v[0:3]
	v_mfma_f32_16x16x32_bf16 v[52:55], v[180:183], v[148:151], v[52:55]
	v_mfma_f32_16x16x32_bf16 v[48:51], v[188:191], v[148:151], v[48:51]
	v_mfma_f32_16x16x32_bf16 v[36:39], v[180:183], v[156:159], v[36:39]
	v_mfma_f32_16x16x32_bf16 v[32:35], v[188:191], v[156:159], v[32:35]
	v_mfma_f32_16x16x32_bf16 v[20:23], v[180:183], v[164:167], v[20:23]
	v_mfma_f32_16x16x32_bf16 v[16:19], v[188:191], v[164:167], v[16:19]
	v_mfma_f32_16x16x32_bf16 v[4:7], v[180:183], v[172:175], v[4:7]
	v_mfma_f32_16x16x32_bf16 v[0:3], v[188:191], v[172:175], v[0:3]
	s_setprio 0
	s_add_i32 s52, s52, 2
	s_add_u32 s30, s30, 0x100
	s_addc_u32 s31, s31, 0
	s_add_u32 s27, s27, 0x100
	s_addc_u32 s33, s33, 0
	s_cmp_gt_u32 s52, 5
	s_barrier
	s_cbranch_scc0 .LBB0_2484
	v_mov_b32_e32 v128, v252
	s_lshl_b32 s1, s28, 8
	v_readfirstlane_b32 s0, v128
	s_ashr_i32 s15, s0, 2
	s_andn2_b32 s15, s15, 63
	s_lshr_b32 s0, s0, 1
	s_add_i32 s15, s15, s1
	s_and_b32 s0, s0, 0x60
	s_lshl_b32 s1, s26, 8
	v_and_or_b32 v218, v128, 15, s15
	v_lshrrev_b32_e32 v128, 1, v128
	s_or_b32 s0, s0, s1
	v_and_b32_e32 v129, 64, v195
	v_and_or_b32 v216, v128, 24, s0
	v_xor_b32_e32 v128, 16, v195
	v_add_u32_e32 v129, 64, v129
	v_cmp_lt_i32_e32 vcc, v128, v129
	v_ashrrev_i32_e32 v219, 31, v218
	v_ashrrev_i32_e32 v217, 31, v216
	v_cndmask_b32_e32 v128, v195, v128, vcc
	v_lshlrev_b32_e32 v200, 2, v128
	v_xor_b32_e32 v128, 32, v195
	v_cmp_lt_i32_e32 vcc, v128, v129
	v_or_b32_e32 v220, 0x80, v216
	v_ashrrev_i32_e32 v221, 31, v220
	v_cndmask_b32_e32 v128, v195, v128, vcc
	v_lshlrev_b32_e32 v199, 2, v128
	v_lshlrev_b64 v[128:129], 10, v[218:219]
	v_lshl_add_u64 v[130:131], v[128:129], 0, v[216:217]
	v_lshlrev_b64 v[130:131], 1, v[130:131]
	v_lshl_add_u64 v[246:247], s[8:9], 0, v[130:131]
	v_lshl_add_u64 v[250:251], s[10:11], 0, v[130:131]
	global_load_dwordx4 v[188:191], v[246:247], off
	global_load_dwordx4 v[180:183], v[246:247], off offset:256
	global_load_dwordx4 v[184:187], v[250:251], off
	v_or_b32_e32 v242, 16, v218
	v_lshl_add_u64 v[128:129], v[128:129], 0, v[220:221]
	v_ashrrev_i32_e32 v243, 31, v242
	v_lshl_add_u64 v[248:249], v[128:129], 1, s[10:11]
	v_lshlrev_b64 v[128:129], 10, v[242:243]
	v_or_b32_e32 v234, 32, v218
	v_lshl_add_u64 v[130:131], v[128:129], 0, v[216:217]
	v_lshl_add_u64 v[128:129], v[128:129], 0, v[220:221]
	v_ashrrev_i32_e32 v235, 31, v234
	v_lshlrev_b64 v[130:131], 1, v[130:131]
	v_lshl_add_u64 v[240:241], v[128:129], 1, s[10:11]
	v_lshlrev_b64 v[128:129], 10, v[234:235]
	v_or_b32_e32 v226, 48, v218
	v_lshl_add_u64 v[238:239], s[8:9], 0, v[130:131]
	v_lshl_add_u64 v[244:245], s[10:11], 0, v[130:131]
	v_lshl_add_u64 v[130:131], v[128:129], 0, v[216:217]
	v_lshl_add_u64 v[128:129], v[128:129], 0, v[220:221]
	v_ashrrev_i32_e32 v227, 31, v226
	v_lshlrev_b64 v[130:131], 1, v[130:131]
	v_lshl_add_u64 v[232:233], v[128:129], 1, s[10:11]
	v_lshlrev_b64 v[128:129], 10, v[226:227]
	v_lshl_add_u64 v[228:229], s[8:9], 0, v[130:131]
	v_lshl_add_u64 v[236:237], s[10:11], 0, v[130:131]
	v_lshl_add_u64 v[130:131], v[128:129], 0, v[216:217]
	v_lshlrev_b64 v[130:131], 1, v[130:131]
	v_lshl_add_u64 v[132:133], v[128:129], 0, v[220:221]
	v_lshl_add_u64 v[222:223], s[8:9], 0, v[130:131]
	v_lshl_add_u64 v[230:231], s[10:11], 0, v[130:131]
	v_lshl_add_u64 v[224:225], v[132:133], 1, s[10:11]
	global_load_dwordx4 v[176:179], v[248:249], off
	global_load_dwordx4 v[172:175], v[238:239], off
	global_load_dwordx4 v[164:167], v[238:239], off offset:256
	global_load_dwordx4 v[168:171], v[244:245], off
	global_load_dwordx4 v[160:163], v[240:241], off
	global_load_dwordx4 v[156:159], v[228:229], off
	global_load_dwordx4 v[132:135], v[224:225], off
	global_load_dwordx4 v[152:155], v[236:237], off
	global_load_dwordx4 v[144:147], v[232:233], off
	global_load_dwordx4 v[148:151], v[228:229], off offset:256
	global_load_dwordx4 v[136:139], v[230:231], off
	global_load_dwordx4 v[140:143], v[222:223], off
	global_load_dwordx4 v[128:131], v[222:223], off offset:256
	v_cmp_gt_u32_e32 vcc, 16, v195
	s_waitcnt vmcnt(0)
	v_lshlrev_b32_e32 v202, 16, v188
	v_and_b32_e32 v203, 0xffff0000, v188
	v_lshlrev_b32_e32 v204, 16, v184
	v_and_b32_e32 v205, 0xffff0000, v184
	v_lshlrev_b32_e32 v188, 16, v189
	v_and_b32_e32 v189, 0xffff0000, v189
	v_lshlrev_b32_e32 v184, 16, v185
	v_and_b32_e32 v185, 0xffff0000, v185
	v_pk_add_f32 v[202:203], v[202:203], v[204:205]
	v_pk_add_f32 v[184:185], v[188:189], v[184:185]
	v_pk_add_f32 v[188:189], v[124:125], v[202:203]
	v_pk_add_f32 v[184:185], v[126:127], v[184:185]
	v_lshlrev_b32_e32 v124, 16, v190
	v_and_b32_e32 v125, 0xffff0000, v190
	v_lshlrev_b32_e32 v126, 16, v186
	v_and_b32_e32 v127, 0xffff0000, v186
	v_pk_add_f32 v[124:125], v[124:125], v[126:127]
	v_lshlrev_b32_e32 v126, 16, v191
	v_and_b32_e32 v127, 0xffff0000, v191
	v_lshlrev_b32_e32 v186, 16, v187
	v_and_b32_e32 v187, 0xffff0000, v187
	v_pk_add_f32 v[126:127], v[126:127], v[186:187]
	v_pk_add_f32 v[190:191], v[120:121], v[124:125]
	v_cvt_pk_bf16_f32 v120, v188, v189
	v_pk_add_f32 v[186:187], v[122:123], v[126:127]
	v_and_b32_e32 v123, 0xffff0000, v120
	v_lshlrev_b32_e32 v122, 16, v120
	v_pk_add_f32 v[122:123], v[188:189], v[122:123] neg_lo:[0,1] neg_hi:[0,1]
	v_cvt_pk_bf16_f32 v121, v184, v185
	v_cvt_pk_bf16_f32 v124, v122, v123
	v_and_b32_e32 v123, 0xffff0000, v121
	v_lshlrev_b32_e32 v122, 16, v121
	v_pk_add_f32 v[122:123], v[184:185], v[122:123] neg_lo:[0,1] neg_hi:[0,1]
	s_nop 0
	v_cvt_pk_bf16_f32 v125, v122, v123
	v_cvt_pk_bf16_f32 v122, v190, v191
	v_cvt_pk_bf16_f32 v123, v186, v187
	v_and_b32_e32 v127, 0xffff0000, v122
	v_lshlrev_b32_e32 v126, 16, v122
	v_and_b32_e32 v203, 0xffff0000, v123
	v_lshlrev_b32_e32 v202, 16, v123
	v_pk_add_f32 v[126:127], v[190:191], v[126:127] neg_lo:[0,1] neg_hi:[0,1]
	v_pk_add_f32 v[202:203], v[186:187], v[202:203] neg_lo:[0,1] neg_hi:[0,1]
	v_cvt_pk_bf16_f32 v126, v126, v127
	v_cvt_pk_bf16_f32 v127, v202, v203
	global_store_dwordx4 v[246:247], v[120:123], off
	global_store_dwordx4 v[250:251], v[124:127], off
	s_nop 0
	v_pk_mul_f32 v[122:123], v[190:191], v[190:191]
	v_pk_mul_f32 v[120:121], v[186:187], v[186:187]
	v_pk_fma_f32 v[122:123], v[188:189], v[188:189], v[122:123]
	v_pk_fma_f32 v[120:121], v[184:185], v[184:185], v[120:121]
	v_add_f32_e32 v122, v122, v123
	v_add_f32_e32 v120, v120, v122
	v_add_f32_e32 v120, v121, v120
	ds_bpermute_b32 v121, v200, v120
	s_waitcnt lgkmcnt(0)
	v_add_f32_e32 v122, v120, v121
	ds_bpermute_b32 v123, v199, v122
	v_lshl_add_u64 v[120:121], v[218:219], 2, s[12:13]
	s_and_saveexec_b64 s[26:27], vcc
	s_cbranch_execz .LBB0_2487
	s_waitcnt lgkmcnt(0)
	v_add_f32_e32 v122, v122, v123
	global_atomic_add_f32 v[120:121], v122, off
